# v26 + attention QK: progressive counted lgkmcnt waits (6/4/2/0) between the K-fragment MFMA pairs instead of one lgkmcnt(0)
# speedup vs baseline: 1.0100x; 1.0032x over previous
; __device__ __forceinline__ void diff_unit(int b, int hd, int qb, const bf16_t* Q, const bf16_t* K, const bf16_t* VT, bf16_t* O, const float* biasd, float lam, const float* subg, ALAS unsigned char* lds) {
;     ...
;     const int tid = tid_, lane = tid & 63, wid = __builtin_amdgcn_readfirstlane(tid >> 6), r32 = lane & 31, hi = lane >> 5;
;     const int map = wid >> 2, w4 = wid & 3, q0 = qb * 128 + w4 * 32, qpos = q0 + r32;
;     if (wid >= 4) __builtin_amdgcn_s_setprio(1);
;     const size_t tok0 = (size_t)b * SEQ;
;     ALAS float* btab = (ALAS float*)(lds + 73728);
;     btab[tid] = biasd[(2 * hd) * 256 + tid];
;     const ALAS float* bt = btab + map * 256;
;     const float cb = biasd[(2 * hd + map) * 256 + 255];
;     bf16x8 qf[4];
;     { const bf16_t* qp = Q + (tok0 + qpos) * 1024 + (2 * hd + map) * 64 + hi * 8;
; #pragma unroll
;       for (int d0 = 0; d0 < 4; ++d0) qf[d0] = *(const bf16x8*)(qp + d0 * 16); }
;     const int NT = 2 * (qb + 1);
;     const bf16_t* kg[2]; const bf16_t* vg[2]; int kl[2], vl[2];
; #pragma unroll
;     for (int i = 0; i < 2; ++i) { const int c = tid + 512 * i; const int key = c >> 4, part = c & 15;
;         kg[i] = K + (tok0 + key) * 1024 + hd * 128 + part * 8; kl[i] = ((part >> 3) * 64 + key) * ROWB + (part & 7) * 16;
;         const int d = c >> 3, pv = c & 7; vg[i] = VT + (size_t)(hd * 128 + d) * MTOK + tok0 + pv * 8; vl[i] = 18432 + d * ROWB + pv * 16; }
;     u32x4 kr[2], vr[2];
; #pragma unroll
;     for (int i = 0; i < 2; ++i) { kr[i] = *(const u32x4*)(kg[i]); vr[i] = *(const u32x4*)(vg[i]); }
;     f32x16 o[4]; float mref = 0.f, lsum = 0.f;
; #pragma unroll
;     for (int d = 0; d < 4; ++d)
; #pragma unroll
;         for (int r = 0; r < 16; ++r) o[d][r] = 0.f;
;     for (int t = 0; t < NT; ++t) {
;         ALAS unsigned char* buf = lds + (t & 1) * 36864;
; #pragma unroll
;         for (int i = 0; i < 2; ++i) { *(ALAS u32x4*)(buf + kl[i]) = kr[i]; *(ALAS u32x4*)(buf + vl[i]) = vr[i]; }
;         __syncthreads();
;         if (t + 1 < NT) {
; #pragma unroll
;             for (int i = 0; i < 2; ++i) { kr[i] = *(const u32x4*)(kg[i] + (size_t)(t + 1) * 64 * 1024); vr[i] = *(const u32x4*)(vg[i] + (t + 1) * 64); }
;         }
;         const int kbase = 64 * t;
;         if (kbase <= q0 + 31) {
;             const bool far = (q0 - (kbase + 63)) >= 128;
;             f32x16 s0, s1; const float ci = (far ? cb : 0.f) - mref;
.LBB0_497:
	s_ashr_i32 s9, s1, 6
	s_and_b32 s6, s1, 3
	s_and_b32 s9, s9, -8
	s_or_b32 s6, s9, s6
	s_and_b32 s8, s1, 0x100
	s_xor_b32 s9, s6, 7
	s_cmp_eq_u32 s8, 0
	s_cselect_b32 s14, s6, s9
	s_bfe_u32 s10, s1, 0x30002
	v_lshl_add_u32 v0, s10, 9, v135
	v_ashrrev_i32_e32 v1, 31, v0
	v_lshl_add_u64 v[0:1], v[0:1], 2, s[96:97]
	global_load_dword v0, v[0:1], off
	s_and_b32 s8, s4, 3
	s_lshl_b32 s12, s14, 7
	s_lshl_b32 s13, s8, 5
	v_and_b32_e32 v70, 31, v135
	s_or_b32 s15, s13, s12
	v_or_b32_e32 v136, s15, v70
	s_lshl_b32 s4, s1, 7
	v_lshl_add_u32 v1, v135, 2, 0
	s_and_b32 s4, s4, 0x7000
	v_add_u32_e32 v1, 0x12000, v1
	v_ashrrev_i32_e32 v137, 31, v136
	v_bfe_u32 v2, v135, 5, 1
	s_ashr_i32 s9, s7, 8
	s_lshl_b32 s6, s10, 7
	s_cmp_lt_i32 s14, 0
	v_lshlrev_b32_e32 v134, 3, v2
	v_lshlrev_b32_e32 v130, 4, v2
	s_waitcnt vmcnt(0)
	ds_write_b32 v1, v0
	v_lshl_add_u64 v[0:1], v[136:137], 0, s[4:5]
	v_lshlrev_b64 v[132:133], 10, v[0:1]
	s_cbranch_scc1 .LBB0_511
	s_lshl_b32 s10, s10, 1
	s_add_i32 s17, s9, s10
	s_lshl_b32 s10, s17, 8
	s_ashr_i32 s11, s10, 31
	s_and_b32 s16, s7, 0x3fffff00
	s_lshl_b64 s[10:11], s[10:11], 2
	s_add_u32 s10, s96, s10
	s_addc_u32 s11, s97, s11
	global_load_dword v137, v145, s[10:11] offset:1020
	s_lshl_b32 s10, s6, 1
	s_add_u32 s10, s82, s10
	v_lshlrev_b32_e32 v1, 4, v135
	s_addc_u32 s11, s83, 0
	v_and_b32_e32 v144, 0xf0, v1
	v_lshlrev_b32_e32 v0, 3, v135
	v_lshl_add_u64 v[2:3], s[10:11], 0, v[144:145]
	s_lshl_b32 s10, s4, 1
	v_and_b32_e32 v8, 64, v0
	s_add_u32 s10, s20, s10
	v_ashrrev_i32_e32 v64, 4, v135
	v_and_b32_e32 v20, 0x70, v1
	s_addc_u32 s11, s21, 0
	v_mov_b32_e32 v21, v145
	v_add_u32_e32 v6, v8, v64
	s_movk_i32 s18, 0x90
	v_lshl_add_u64 v[4:5], s[10:11], 0, v[20:21]
	v_mad_u64_u32 v[138:139], s[10:11], v6, s18, v[20:21]
	v_ashrrev_i32_e32 v21, 3, v135
	v_add_u32_e32 v6, s6, v21
	v_add_u32_e32 v9, 0x200, v135
	v_ashrrev_i32_e32 v7, 31, v6
	v_ashrrev_i32_e32 v66, 4, v9
	v_ashrrev_i32_e32 v65, 31, v64
	v_lshlrev_b64 v[6:7], 16, v[6:7]
	v_ashrrev_i32_e32 v67, 31, v66
	v_lshl_add_u64 v[0:1], v[64:65], 0, s[4:5]
	v_lshl_add_u64 v[140:141], v[4:5], 0, v[6:7]
	v_lshl_add_u64 v[6:7], v[66:67], 0, s[4:5]
	v_lshlrev_b64 v[0:1], 11, v[0:1]
	v_lshlrev_b64 v[6:7], 11, v[6:7]
	v_lshl_add_u64 v[0:1], v[2:3], 0, v[0:1]
	v_lshl_add_u64 v[2:3], v[2:3], 0, v[6:7]
	v_add_u32_e32 v6, v66, v8
	v_ashrrev_i32_e32 v22, 3, v9
	v_mad_u64_u32 v[142:143], s[10:11], v6, s18, v[20:21]
	v_add_u32_e32 v6, s6, v22
	v_ashrrev_i32_e32 v7, 31, v6
	v_lshlrev_b64 v[6:7], 16, v[6:7]
	s_lshl_b32 s4, s16, 2
	s_lshl_b32 s16, s17, 6
	v_lshl_add_u64 v[156:157], v[4:5], 0, v[6:7]
	v_lshl_add_u64 v[4:5], v[132:133], 1, s[80:81]
	s_ashr_i32 s17, s16, 31
	v_lshl_add_u64 v[4:5], s[16:17], 1, v[4:5]
	v_mov_b32_e32 v131, v145
	v_lshl_add_u64 v[4:5], v[4:5], 0, v[130:131]
	global_load_dwordx4 v[96:99], v[4:5], off offset:96
	global_load_dwordx4 v[100:103], v[4:5], off offset:64
	global_load_dwordx4 v[104:107], v[4:5], off offset:32
	global_load_dwordx4 v[108:111], v[4:5], off
	s_nop 0
	global_load_dwordx4 v[4:7], v[156:157], off
	global_load_dwordx4 v[8:11], v[2:3], off
	global_load_dwordx4 v[12:15], v[140:141], off
	global_load_dwordx4 v[16:19], v[0:1], off
	v_lshlrev_b32_e32 v24, 1, v70
	v_lshrrev_b32_e32 v25, 1, v135
	v_and_b32_e32 v23, 19, v135
	v_and_b32_e32 v24, 8, v24
	v_and_b32_e32 v25, 4, v25
	v_or3_b32 v23, v25, v23, v24
	v_mul_u32_u24_e32 v139, 0x90, v23
	v_add_u32_e32 v23, 0, v138
	v_mad_u64_u32 v[158:159], s[16:17], v21, s18, v[20:21]
	s_add_i32 s10, s4, 0
	s_mov_b32 s4, 0x20000
	v_mad_u64_u32 v[160:161], s[16:17], v22, s18, v[20:21]
	v_add_co_u32_e32 v0, vcc, s4, v0
	s_add_i32 s10, s10, 0x12000
	s_nop 0
	v_addc_co_u32_e32 v1, vcc, 0, v1, vcc
	s_mul_i32 s11, s9, 0x2400
	s_cmpk_gt_i32 s15, 0xbe
	s_waitcnt vmcnt(0)
	ds_write_b128 v23, v[16:19]
	v_add_u32_e32 v16, 0, v158
	ds_write_b128 v16, v[12:15] offset:18432
	v_add_u32_e32 v12, 0, v142
	ds_write_b128 v12, v[8:11]
	v_add_u32_e32 v8, 0, v160
	ds_write_b128 v8, v[4:7] offset:18432
	s_waitcnt lgkmcnt(0)
	s_barrier
	global_load_dwordx4 v[112:115], v[0:1], off
	global_load_dwordx4 v[116:119], v[140:141], off offset:128
	v_add_co_u32_e32 v0, vcc, s4, v2
	s_nop 1
	v_addc_co_u32_e32 v1, vcc, 0, v3, vcc
	global_load_dwordx4 v[120:123], v[0:1], off
	global_load_dwordx4 v[124:127], v[156:157], off offset:128
	s_cselect_b64 vcc, -1, 0
	s_add_i32 s4, s11, 0
	v_add3_u32 v1, s4, v139, v130
	ds_read_b128 v[32:35], v1 offset:0
	ds_read_b128 v[36:39], v1 offset:4608
	ds_read_b128 v[40:43], v1 offset:32
	ds_read_b128 v[44:47], v1 offset:4640
	ds_read_b128 v[48:51], v1 offset:64
	ds_read_b128 v[52:55], v1 offset:4672
	ds_read_b128 v[56:59], v1 offset:96
	ds_read_b128 v[60:63], v1 offset:4704
	v_cndmask_b32_e32 v0, 0, v137, vcc
	v_mov_b32_e32 v1, v0
	v_mov_b32_e32 v2, v0
	v_mov_b32_e32 v3, v0
	v_mov_b32_e32 v4, v0
	v_mov_b32_e32 v5, v0
	v_mov_b32_e32 v6, v0
	v_mov_b32_e32 v7, v0
	v_mov_b32_e32 v8, v0
	v_mov_b32_e32 v9, v0
	v_mov_b32_e32 v10, v0
	v_mov_b32_e32 v11, v0
	v_mov_b32_e32 v12, v0
	v_mov_b32_e32 v13, v0
	v_mov_b32_e32 v14, v0
	v_mov_b32_e32 v15, v0
	s_waitcnt lgkmcnt(6)
	s_nop 1
	v_mfma_f32_32x32x16_bf16 v[16:31], v[32:35], v[108:111], v[0:15]
	s_and_b64 vcc, exec, vcc
	v_mfma_f32_32x32x16_bf16 v[0:15], v[36:39], v[108:111], v[0:15]
	s_waitcnt lgkmcnt(4)
	v_mfma_f32_32x32x16_bf16 v[16:31], v[40:43], v[104:107], v[16:31]
	v_mfma_f32_32x32x16_bf16 v[0:15], v[44:47], v[104:107], v[0:15]
	s_waitcnt lgkmcnt(2)
	v_mfma_f32_32x32x16_bf16 v[16:31], v[48:51], v[100:103], v[16:31]
	v_mfma_f32_32x32x16_bf16 v[0:15], v[52:55], v[100:103], v[0:15]
	s_waitcnt lgkmcnt(0)
	v_mfma_f32_32x32x16_bf16 v[16:31], v[56:59], v[96:99], v[16:31]
	v_mfma_f32_32x32x16_bf16 v[0:15], v[60:63], v[96:99], v[0:15]
	s_cbranch_vccnz .LBB0_500
; #define ALAS __attribute__((address_space(3)))
; __device__ __forceinline__ void near_bias(f32x16& s0, f32x16& s1, const ALAS float* bt, int qpos, int kbase, int hi) {
; #pragma unroll
;     for (int r = 0; r < 16; ++r) {
;         const int d0 = qpos - (kbase + (r & 7) + 8 * hi + 16 * (r >> 3)), d1 = d0 - 32;
;         const float b0 = bt[min(max(d0, 0), 255)], b1 = bt[min(max(d1, 0), 255)];
;         s0[r] = d0 < 0 ? NEG : s0[r] + b0; s1[r] = d1 < 0 ? NEG : s1[r] + b1;
;     }
; }
	v_xad_u32 v69, v134, -1, v136
	v_med3_i32 v34, v69, 0, v204
	v_lshl_add_u32 v35, v34, 2, s10
	v_max_i32_e32 v34, 32, v69
	v_subrev_u32_e32 v34, 32, v34
	v_min_u32_e32 v34, 0xff, v34
	v_or_b32_e32 v37, 2, v134
	v_lshl_add_u32 v36, v34, 2, s10
	v_or_b32_e32 v34, 3, v134
	v_sub_u32_e32 v72, v136, v37
	v_sub_u32_e32 v71, v136, v34
	v_med3_i32 v34, v72, 0, v204
	v_lshl_add_u32 v37, v34, 2, s10
	v_max_i32_e32 v34, 32, v72
	v_subrev_u32_e32 v34, 32, v34
	v_min_u32_e32 v34, 0xff, v34
	v_sub_u32_e32 v68, v136, v134
	v_lshl_add_u32 v38, v34, 2, s10
	v_max_i32_e32 v34, 32, v71
	v_max_i32_e32 v33, 32, v68
	v_subrev_u32_e32 v34, 32, v34
	v_subrev_u32_e32 v33, 32, v33
	v_min_u32_e32 v34, 0xff, v34
	v_med3_i32 v32, v68, 0, v204
	v_min_u32_e32 v33, 0xff, v33
	v_lshl_add_u32 v39, v34, 2, s10
	v_med3_i32 v34, v71, 0, v204
	v_lshl_add_u32 v32, v32, 2, s10
	v_lshl_add_u32 v33, v33, 2, s10
	v_lshl_add_u32 v40, v34, 2, s10
	ds_read_b32 v34, v32
	ds_read_b32 v32, v33
	ds_read_b32 v35, v35
	ds_read_b32 v33, v36
	ds_read_b32 v36, v37
	ds_read_b32 v38, v38
	ds_read_b32 v39, v39
	ds_read_b32 v37, v40
	v_or_b32_e32 v40, 5, v134
	v_sub_u32_e32 v73, v136, v40
	v_max_i32_e32 v42, 32, v73
	v_subrev_u32_e32 v42, 32, v42
	v_min_u32_e32 v42, 0xff, v42
	v_lshl_add_u32 v43, v42, 2, s10
	v_med3_i32 v42, v73, 0, v204
	v_or_b32_e32 v45, 6, v134
	v_lshl_add_u32 v44, v42, 2, s10
	v_or_b32_e32 v42, 7, v134
	v_sub_u32_e32 v76, v136, v45
	v_sub_u32_e32 v75, v136, v42
	v_med3_i32 v42, v76, 0, v204
	v_lshl_add_u32 v45, v42, 2, s10
	v_max_i32_e32 v42, 32, v76
	v_subrev_u32_e32 v42, 32, v42
	v_or_b32_e32 v41, 4, v134
	v_min_u32_e32 v42, 0xff, v42
	v_sub_u32_e32 v74, v136, v41
	v_lshl_add_u32 v46, v42, 2, s10
	v_max_i32_e32 v42, 32, v75
	v_max_i32_e32 v41, 32, v74
	v_subrev_u32_e32 v42, 32, v42
	v_subrev_u32_e32 v41, 32, v41
	v_min_u32_e32 v42, 0xff, v42
	v_med3_i32 v40, v74, 0, v204
	v_min_u32_e32 v41, 0xff, v41
	v_lshl_add_u32 v47, v42, 2, s10
	v_med3_i32 v42, v75, 0, v204
	v_lshl_add_u32 v40, v40, 2, s10
	v_lshl_add_u32 v41, v41, 2, s10
	v_lshl_add_u32 v48, v42, 2, s10
	ds_read_b32 v40, v40
	ds_read_b32 v42, v41
	ds_read_b32 v43, v43
	ds_read_b32 v41, v44
	ds_read_b32 v44, v45
	ds_read_b32 v46, v46
	ds_read_b32 v47, v47
	ds_read_b32 v45, v48
	v_or_b32_e32 v48, 17, v134
	v_sub_u32_e32 v77, v136, v48
	v_max_i32_e32 v50, 32, v77
	v_subrev_u32_e32 v50, 32, v50
	v_min_u32_e32 v50, 0xff, v50
	v_lshl_add_u32 v51, v50, 2, s10
	v_med3_i32 v50, v77, 0, v204
	v_or_b32_e32 v53, 18, v134
	v_lshl_add_u32 v52, v50, 2, s10
	v_or_b32_e32 v50, 19, v134
	v_sub_u32_e32 v80, v136, v53
	v_sub_u32_e32 v79, v136, v50
	v_med3_i32 v50, v80, 0, v204
	v_lshl_add_u32 v53, v50, 2, s10
	v_max_i32_e32 v50, 32, v80
	v_subrev_u32_e32 v50, 32, v50
	v_or_b32_e32 v49, 16, v134
	v_min_u32_e32 v50, 0xff, v50
	v_sub_u32_e32 v78, v136, v49
	v_lshl_add_u32 v54, v50, 2, s10
	v_max_i32_e32 v50, 32, v79
	v_max_i32_e32 v49, 32, v78
	v_subrev_u32_e32 v50, 32, v50
	v_subrev_u32_e32 v49, 32, v49
	v_min_u32_e32 v50, 0xff, v50
	v_med3_i32 v48, v78, 0, v204
	v_min_u32_e32 v49, 0xff, v49
	v_lshl_add_u32 v55, v50, 2, s10
	v_med3_i32 v50, v79, 0, v204
	v_lshl_add_u32 v48, v48, 2, s10
	v_lshl_add_u32 v49, v49, 2, s10
	v_lshl_add_u32 v56, v50, 2, s10
	ds_read_b32 v48, v48
	ds_read_b32 v50, v49
	ds_read_b32 v51, v51
	ds_read_b32 v49, v52
	ds_read_b32 v52, v53
	ds_read_b32 v54, v54
	ds_read_b32 v55, v55
	ds_read_b32 v53, v56
	v_or_b32_e32 v56, 21, v134
	v_sub_u32_e32 v81, v136, v56
	v_max_i32_e32 v58, 32, v81
	v_subrev_u32_e32 v58, 32, v58
	v_min_u32_e32 v58, 0xff, v58
	v_lshl_add_u32 v59, v58, 2, s10
	v_med3_i32 v58, v81, 0, v204
	v_or_b32_e32 v61, 22, v134
	v_lshl_add_u32 v60, v58, 2, s10
	v_or_b32_e32 v58, 23, v134
	v_sub_u32_e32 v84, v136, v61
	v_sub_u32_e32 v83, v136, v58
	v_med3_i32 v58, v84, 0, v204
	v_lshl_add_u32 v61, v58, 2, s10
	v_max_i32_e32 v58, 32, v84
	v_or_b32_e32 v57, 20, v134
	v_subrev_u32_e32 v58, 32, v58
	v_sub_u32_e32 v82, v136, v57
	v_min_u32_e32 v58, 0xff, v58
	v_max_i32_e32 v57, 32, v82
	v_lshl_add_u32 v62, v58, 2, s10
	v_max_i32_e32 v58, 32, v83
	v_subrev_u32_e32 v57, 32, v57
	v_subrev_u32_e32 v58, 32, v58
	v_med3_i32 v56, v82, 0, v204
	v_min_u32_e32 v57, 0xff, v57
	v_min_u32_e32 v58, 0xff, v58
	v_lshl_add_u32 v56, v56, 2, s10
	v_lshl_add_u32 v57, v57, 2, s10
	v_lshl_add_u32 v63, v58, 2, s10
	v_med3_i32 v58, v83, 0, v204
	v_lshl_add_u32 v85, v58, 2, s10
	ds_read_b32 v56, v56
	ds_read_b32 v58, v57
	ds_read_b32 v59, v59
	ds_read_b32 v57, v60
	ds_read_b32 v60, v61
	ds_read_b32 v62, v62
	ds_read_b32 v63, v63
	ds_read_b32 v61, v85
	s_waitcnt lgkmcnt(14)
; __device__ __forceinline__ void near_bias(f32x16& s0, f32x16& s1, const ALAS float* bt, int qpos, int kbase, int hi) {
;     ...
;         const int d0 = qpos - (kbase + (r & 7) + 8 * hi + 16 * (r >> 3)), d1 = d0 - 32;
;         const float b0 = bt[min(max(d0, 0), 255)], b1 = bt[min(max(d1, 0), 255)];
;         s0[r] = d0 < 0 ? NEG : s0[r] + b0; s1[r] = d1 < 0 ? NEG : s1[r] + b1;
	v_pk_add_f32 v[16:17], v[16:17], v[34:35]
	v_cmp_lt_i32_e32 vcc, -1, v69
	s_waitcnt lgkmcnt(4)
	v_pk_add_f32 v[28:29], v[28:29], v[56:57]
	v_pk_add_f32 v[26:27], v[26:27], v[52:53]
	s_waitcnt lgkmcnt(0)
	v_pk_add_f32 v[30:31], v[30:31], v[60:61]
	v_cndmask_b32_e32 v17, v205, v17, vcc
	v_cmp_lt_i32_e32 vcc, -1, v83
	v_pk_add_f32 v[24:25], v[24:25], v[48:49]
	v_pk_add_f32 v[22:23], v[22:23], v[44:45]
	v_cndmask_b32_e32 v31, v205, v31, vcc
	v_cmp_lt_i32_e32 vcc, -1, v84
	v_pk_add_f32 v[20:21], v[20:21], v[40:41]
	v_pk_add_f32 v[18:19], v[18:19], v[36:37]
	v_cndmask_b32_e32 v30, v205, v30, vcc
	v_cmp_lt_i32_e32 vcc, -1, v81
	v_pk_add_f32 v[0:1], v[0:1], v[32:33]
	v_pk_add_f32 v[14:15], v[14:15], v[62:63]
	v_cndmask_b32_e32 v29, v205, v29, vcc
	v_cmp_lt_i32_e32 vcc, -1, v82
	v_pk_add_f32 v[12:13], v[12:13], v[58:59]
	v_pk_add_f32 v[10:11], v[10:11], v[54:55]
	v_cndmask_b32_e32 v28, v205, v28, vcc
	v_cmp_lt_i32_e32 vcc, -1, v79
	v_pk_add_f32 v[8:9], v[8:9], v[50:51]
	v_pk_add_f32 v[6:7], v[6:7], v[46:47]
	v_cndmask_b32_e32 v27, v205, v27, vcc
	v_cmp_lt_i32_e32 vcc, -1, v80
	v_pk_add_f32 v[4:5], v[4:5], v[42:43]
	v_pk_add_f32 v[2:3], v[2:3], v[38:39]
	v_cndmask_b32_e32 v26, v205, v26, vcc
	v_cmp_lt_i32_e32 vcc, -1, v77
	s_nop 1
	v_cndmask_b32_e32 v25, v205, v25, vcc
	v_cmp_lt_i32_e32 vcc, -1, v78
	s_nop 1
	v_cndmask_b32_e32 v24, v205, v24, vcc
	v_cmp_lt_i32_e32 vcc, -1, v75
	s_nop 1
	v_cndmask_b32_e32 v23, v205, v23, vcc
	v_cmp_lt_i32_e32 vcc, -1, v76
	s_nop 1
	v_cndmask_b32_e32 v22, v205, v22, vcc
	v_cmp_lt_i32_e32 vcc, -1, v73
	s_nop 1
	v_cndmask_b32_e32 v21, v205, v21, vcc
	v_cmp_lt_i32_e32 vcc, -1, v74
	s_nop 1
	v_cndmask_b32_e32 v20, v205, v20, vcc
	v_cmp_lt_i32_e32 vcc, -1, v71
	s_nop 1
	v_cndmask_b32_e32 v19, v205, v19, vcc
	v_cmp_lt_i32_e32 vcc, -1, v72
	s_nop 1
	v_cndmask_b32_e32 v18, v205, v18, vcc
	v_cmp_lt_i32_e32 vcc, -1, v68
	s_nop 1
	v_cndmask_b32_e32 v16, v205, v16, vcc
	v_cmp_lt_i32_e32 vcc, 31, v69
	s_nop 1
	v_cndmask_b32_e32 v1, v205, v1, vcc
	v_cmp_lt_i32_e32 vcc, 31, v83
	s_nop 1
	v_cndmask_b32_e32 v15, v205, v15, vcc
	v_cmp_lt_i32_e32 vcc, 31, v84
	s_nop 1
	v_cndmask_b32_e32 v14, v205, v14, vcc
	v_cmp_lt_i32_e32 vcc, 31, v81
	s_nop 1
	v_cndmask_b32_e32 v13, v205, v13, vcc
	v_cmp_lt_i32_e32 vcc, 31, v82
	s_nop 1
	v_cndmask_b32_e32 v12, v205, v12, vcc
	v_cmp_lt_i32_e32 vcc, 31, v79
	s_nop 1
	v_cndmask_b32_e32 v11, v205, v11, vcc
	v_cmp_lt_i32_e32 vcc, 31, v80
	s_nop 1
	v_cndmask_b32_e32 v10, v205, v10, vcc
	v_cmp_lt_i32_e32 vcc, 31, v77
	s_nop 1
	v_cndmask_b32_e32 v9, v205, v9, vcc
	v_cmp_lt_i32_e32 vcc, 31, v78
	s_nop 1
	v_cndmask_b32_e32 v8, v205, v8, vcc
	v_cmp_lt_i32_e32 vcc, 31, v75
	s_nop 1
	v_cndmask_b32_e32 v7, v205, v7, vcc
	v_cmp_lt_i32_e32 vcc, 31, v76
	s_nop 1
	v_cndmask_b32_e32 v6, v205, v6, vcc
	v_cmp_lt_i32_e32 vcc, 31, v73
	s_nop 1
	v_cndmask_b32_e32 v5, v205, v5, vcc
	v_cmp_lt_i32_e32 vcc, 31, v74
	s_nop 1
	v_cndmask_b32_e32 v4, v205, v4, vcc
	v_cmp_lt_i32_e32 vcc, 31, v71
	s_nop 1
	v_cndmask_b32_e32 v3, v205, v3, vcc
	v_cmp_lt_i32_e32 vcc, 31, v72
	s_nop 1
	v_cndmask_b32_e32 v2, v205, v2, vcc
	v_cmp_lt_i32_e32 vcc, 31, v68
	s_nop 1
	v_cndmask_b32_e32 v0, v205, v0, vcc

; #define ALAS __attribute__((address_space(3)))
; __device__ __forceinline__ int kperm(int i) { return (i & 19) | ((i & 4) << 1) | ((i & 8) >> 1); }
; template <int OFF> __device__ __forceinline__ void ldsr(bf16x8& d, unsigned a) { asm volatile("ds_read_b128 %0, %1 offset:%c2" : "=v"(d) : "v"(a), "i"(OFF) : "memory"); }
; __device__ __forceinline__ void lds_wait8(bf16x8 (&a)[8]) { asm volatile("s_waitcnt lgkmcnt(0)" : "+v"(a[0]), "+v"(a[1]), "+v"(a[2]), "+v"(a[3]), "+v"(a[4]), "+v"(a[5]), "+v"(a[6]), "+v"(a[7]) :: "memory"); }
; __device__ __forceinline__ void qk_tile(f32x16& s0, f32x16& s1, float ci, const ALAS unsigned char* Kb, const bf16x8 (&qf)[4], int r32, int hi) {
;     const unsigned p0 = (unsigned)(uintptr_t)(Kb + kperm(r32) * ROWB + hi * 16);
;     bf16x8 a[8];
;     ldsr<0>(a[0], p0); ldsr<32 * ROWB>(a[1], p0); ldsr<32>(a[2], p0); ldsr<32 * ROWB + 32>(a[3], p0);
;     ldsr<64>(a[4], p0); ldsr<32 * ROWB + 64>(a[5], p0); ldsr<96>(a[6], p0); ldsr<32 * ROWB + 96>(a[7], p0);
; #pragma unroll
;     for (int r = 0; r < 16; ++r) { s0[r] = ci; s1[r] = ci; }
;     lds_wait8(a); __builtin_amdgcn_sched_barrier(0);
; #pragma unroll
;     for (int d0 = 0; d0 < 4; ++d0) {
;         s0 = __builtin_amdgcn_mfma_f32_32x32x16_bf16(a[2 * d0], qf[d0], s0, 0, 0, 0);
;         s1 = __builtin_amdgcn_mfma_f32_32x32x16_bf16(a[2 * d0 + 1], qf[d0], s1, 0, 0, 0);
;     }
; __device__ __forceinline__ void diff_unit(int b, int hd, int qb, const bf16_t* Q, const bf16_t* K, const bf16_t* VT, bf16_t* O, const float* biasd, float lam, const float* subg, ALAS unsigned char* lds) {
;     ...
;         if (t + 1 < NT) {
; #pragma unroll
;             for (int i = 0; i < 2; ++i) { kr[i] = *(const u32x4*)(kg[i] + (size_t)(t + 1) * 64 * 1024); vr[i] = *(const u32x4*)(vg[i] + (t + 1) * 64); }
;         }
;         const int kbase = 64 * t;
;         if (kbase <= q0 + 31) {
;             const bool far = (q0 - (kbase + 63)) >= 128;
;             f32x16 s0, s1; const float ci = (far ? cb : 0.f) - mref;
;             qk_tile(s0, s1, ci, buf + map * 9216, qf, r32, hi);
;             if (!far) near_bias(s0, s1, bt, qpos, kbase, hi);
.LBB0_506:
	s_cmp_gt_i32 s17, s15
	s_cbranch_scc1 .LBB0_503
	s_cmpk_gt_i32 s12, 0x7f
	s_cselect_b64 vcc, -1, 0
	s_add_i32 s4, s18, s11
	v_add3_u32 v65, s4, v139, v130
	ds_read_b128 v[172:175], v65 offset:0
	ds_read_b128 v[176:179], v65 offset:4608
	ds_read_b128 v[180:183], v65 offset:32
	ds_read_b128 v[184:187], v65 offset:4640
	ds_read_b128 v[188:191], v65 offset:64
	ds_read_b128 v[192:195], v65 offset:4672
	ds_read_b128 v[196:199], v65 offset:96
	ds_read_b128 v[216:219], v65 offset:4704
	v_cndmask_b32_e32 v64, 0, v137, vcc
	v_sub_f32_e32 v64, v64, v163
	v_mov_b32_e32 v65, v64
	v_mov_b32_e32 v66, v64
	v_mov_b32_e32 v67, v64
	v_mov_b32_e32 v68, v64
	v_mov_b32_e32 v69, v64
	v_mov_b32_e32 v70, v64
	v_mov_b32_e32 v71, v64
	v_mov_b32_e32 v72, v64
	v_mov_b32_e32 v73, v64
	v_mov_b32_e32 v74, v64
	v_mov_b32_e32 v75, v64
	v_mov_b32_e32 v76, v64
	v_mov_b32_e32 v77, v64
	v_mov_b32_e32 v78, v64
	v_mov_b32_e32 v79, v64
	s_waitcnt lgkmcnt(6)
	s_nop 1
	v_mfma_f32_32x32x16_bf16 v[80:95], v[172:175], v[108:111], v[64:79]
	s_and_b64 vcc, exec, vcc
	v_mfma_f32_32x32x16_bf16 v[64:79], v[176:179], v[108:111], v[64:79]
	s_waitcnt lgkmcnt(4)
	v_mfma_f32_32x32x16_bf16 v[80:95], v[180:183], v[104:107], v[80:95]
	v_mfma_f32_32x32x16_bf16 v[64:79], v[184:187], v[104:107], v[64:79]
	s_waitcnt lgkmcnt(2)
	v_mfma_f32_32x32x16_bf16 v[80:95], v[188:191], v[100:103], v[80:95]
	v_mfma_f32_32x32x16_bf16 v[64:79], v[192:195], v[100:103], v[64:79]
	s_waitcnt lgkmcnt(0)
	v_mfma_f32_32x32x16_bf16 v[80:95], v[196:199], v[96:99], v[80:95]
	v_mfma_f32_32x32x16_bf16 v[64:79], v[216:219], v[96:99], v[64:79]
	s_cbranch_vccnz .LBB0_509
	v_add_u32_e32 v161, s12, v159
	v_add_u32_e32 v171, 63, v161
	v_add_u32_e32 v161, 62, v161
	v_med3_i32 v172, v161, 0, v204
	v_lshl_add_u32 v173, v172, 2, s10
	v_max_i32_e32 v172, 32, v161
	v_add_u32_e32 v144, s17, v134
	v_subrev_u32_e32 v172, 32, v172
	v_min_u32_e32 v172, 0xff, v172
	v_or_b32_e32 v175, 2, v144
	v_lshl_add_u32 v174, v172, 2, s10
	v_or_b32_e32 v172, 3, v144
	v_sub_u32_e32 v219, v136, v175
	v_sub_u32_e32 v218, v131, v172
	v_med3_i32 v172, v219, 0, v204
	v_lshl_add_u32 v175, v172, 2, s10
	v_max_i32_e32 v172, 32, v219
	v_subrev_u32_e32 v172, 32, v172
	v_min_u32_e32 v172, 0xff, v172
	v_lshl_add_u32 v176, v172, 2, s10
	v_max_i32_e32 v172, 32, v218
	v_max_i32_e32 v169, 32, v171
	v_subrev_u32_e32 v172, 32, v172
	v_subrev_u32_e32 v169, 32, v169
	v_min_u32_e32 v172, 0xff, v172
	v_med3_i32 v168, v171, 0, v204
	v_min_u32_e32 v169, 0xff, v169
	v_lshl_add_u32 v177, v172, 2, s10
	v_med3_i32 v172, v218, 0, v204
	v_lshl_add_u32 v168, v168, 2, s10
	v_lshl_add_u32 v169, v169, 2, s10
	v_lshl_add_u32 v178, v172, 2, s10
	ds_read_b32 v172, v168
	ds_read_b32 v168, v169
	ds_read_b32 v173, v173
	ds_read_b32 v169, v174
	ds_read_b32 v174, v175
	ds_read_b32 v176, v176
	ds_read_b32 v177, v177
	ds_read_b32 v175, v178
	v_or_b32_e32 v178, 5, v144
	v_sub_u32_e32 v220, v131, v178
	v_max_i32_e32 v180, 32, v220
	v_subrev_u32_e32 v180, 32, v180
	v_min_u32_e32 v180, 0xff, v180
	v_lshl_add_u32 v181, v180, 2, s10
	v_med3_i32 v180, v220, 0, v204
	v_or_b32_e32 v183, 6, v144
	v_lshl_add_u32 v182, v180, 2, s10
	v_or_b32_e32 v180, 7, v144
	v_sub_u32_e32 v223, v136, v183
	v_sub_u32_e32 v222, v131, v180
	v_med3_i32 v180, v223, 0, v204
	v_lshl_add_u32 v183, v180, 2, s10
	v_max_i32_e32 v180, 32, v223
	v_subrev_u32_e32 v180, 32, v180
	v_or_b32_e32 v179, 4, v144
	v_min_u32_e32 v180, 0xff, v180
	v_sub_u32_e32 v221, v136, v179
	v_lshl_add_u32 v184, v180, 2, s10
	v_max_i32_e32 v180, 32, v222
	v_max_i32_e32 v179, 32, v221
	v_subrev_u32_e32 v180, 32, v180
	v_subrev_u32_e32 v179, 32, v179
	v_min_u32_e32 v180, 0xff, v180
	v_med3_i32 v178, v221, 0, v204
	v_min_u32_e32 v179, 0xff, v179
	v_lshl_add_u32 v185, v180, 2, s10
	v_med3_i32 v180, v222, 0, v204
	v_lshl_add_u32 v178, v178, 2, s10
	v_lshl_add_u32 v179, v179, 2, s10
	v_lshl_add_u32 v186, v180, 2, s10
	ds_read_b32 v178, v178
	ds_read_b32 v180, v179
	ds_read_b32 v181, v181
	ds_read_b32 v179, v182
	ds_read_b32 v182, v183
	ds_read_b32 v184, v184
	ds_read_b32 v185, v185
	ds_read_b32 v183, v186
	v_or_b32_e32 v186, 17, v144
	v_sub_u32_e32 v224, v131, v186
	v_max_i32_e32 v188, 32, v224
	v_subrev_u32_e32 v188, 32, v188
	v_min_u32_e32 v188, 0xff, v188
	v_lshl_add_u32 v189, v188, 2, s10
	v_med3_i32 v188, v224, 0, v204
	v_or_b32_e32 v191, 18, v144
	v_lshl_add_u32 v190, v188, 2, s10
	v_or_b32_e32 v188, 19, v144
	v_sub_u32_e32 v227, v136, v191
	v_sub_u32_e32 v226, v131, v188
	v_med3_i32 v188, v227, 0, v204
	v_lshl_add_u32 v191, v188, 2, s10
	v_max_i32_e32 v188, 32, v227
	v_subrev_u32_e32 v188, 32, v188
	v_or_b32_e32 v187, 16, v144
	v_min_u32_e32 v188, 0xff, v188
	v_sub_u32_e32 v225, v136, v187
	v_lshl_add_u32 v192, v188, 2, s10
	v_max_i32_e32 v188, 32, v226
	v_max_i32_e32 v187, 32, v225
	v_subrev_u32_e32 v188, 32, v188
	v_subrev_u32_e32 v187, 32, v187
	v_min_u32_e32 v188, 0xff, v188
	v_med3_i32 v186, v225, 0, v204
	v_min_u32_e32 v187, 0xff, v187
	v_lshl_add_u32 v193, v188, 2, s10
	v_med3_i32 v188, v226, 0, v204
	v_lshl_add_u32 v186, v186, 2, s10
	v_lshl_add_u32 v187, v187, 2, s10
	v_lshl_add_u32 v194, v188, 2, s10
	ds_read_b32 v186, v186
	ds_read_b32 v188, v187
	ds_read_b32 v189, v189
	ds_read_b32 v187, v190
	ds_read_b32 v190, v191
	ds_read_b32 v192, v192
	ds_read_b32 v193, v193
	ds_read_b32 v191, v194
	v_or_b32_e32 v194, 21, v144
	v_sub_u32_e32 v228, v131, v194
	v_max_i32_e32 v196, 32, v228
	v_subrev_u32_e32 v196, 32, v196
	v_min_u32_e32 v196, 0xff, v196
	v_lshl_add_u32 v197, v196, 2, s10
	v_med3_i32 v196, v228, 0, v204
	v_or_b32_e32 v195, 20, v144
	v_lshl_add_u32 v198, v196, 2, s10
	v_or_b32_e32 v196, 23, v144
	v_or_b32_e32 v144, 22, v144
	v_sub_u32_e32 v144, v136, v144
	v_sub_u32_e32 v230, v131, v196
	v_med3_i32 v196, v144, 0, v204
	v_lshl_add_u32 v199, v196, 2, s10
	v_max_i32_e32 v196, 32, v144
	v_subrev_u32_e32 v196, 32, v196
	v_sub_u32_e32 v229, v136, v195
	v_min_u32_e32 v196, 0xff, v196
	v_max_i32_e32 v195, 32, v229
	v_lshl_add_u32 v216, v196, 2, s10
	v_max_i32_e32 v196, 32, v230
	v_subrev_u32_e32 v195, 32, v195
	v_subrev_u32_e32 v196, 32, v196
	v_med3_i32 v194, v229, 0, v204
	v_min_u32_e32 v195, 0xff, v195
	v_min_u32_e32 v196, 0xff, v196
	v_lshl_add_u32 v194, v194, 2, s10
	v_lshl_add_u32 v195, v195, 2, s10
	v_lshl_add_u32 v217, v196, 2, s10
	v_med3_i32 v196, v230, 0, v204
	v_lshl_add_u32 v231, v196, 2, s10
	ds_read_b32 v194, v194
	ds_read_b32 v196, v195
	ds_read_b32 v197, v197
	ds_read_b32 v195, v198
	ds_read_b32 v198, v199
	ds_read_b32 v216, v216
	ds_read_b32 v217, v217
	ds_read_b32 v199, v231
	v_cmp_lt_i32_e32 vcc, -1, v230
	s_waitcnt lgkmcnt(4)
; __device__ __forceinline__ void near_bias(f32x16& s0, f32x16& s1, const ALAS float* bt, int qpos, int kbase, int hi) {
;     ...
;         const int d0 = qpos - (kbase + (r & 7) + 8 * hi + 16 * (r >> 3)), d1 = d0 - 32;
;         const float b0 = bt[min(max(d0, 0), 255)], b1 = bt[min(max(d1, 0), 255)];
;         s0[r] = d0 < 0 ? NEG : s0[r] + b0; s1[r] = d1 < 0 ? NEG : s1[r] + b1;
	v_pk_add_f32 v[92:93], v[92:93], v[194:195]
	v_pk_add_f32 v[90:91], v[90:91], v[190:191]
	v_pk_add_f32 v[88:89], v[88:89], v[186:187]
	s_waitcnt lgkmcnt(0)
	v_pk_add_f32 v[94:95], v[94:95], v[198:199]
	v_pk_add_f32 v[86:87], v[86:87], v[182:183]
	v_cndmask_b32_e32 v95, v205, v95, vcc
	v_cmp_lt_i32_e32 vcc, -1, v144
	v_pk_add_f32 v[84:85], v[84:85], v[178:179]
	v_pk_add_f32 v[82:83], v[82:83], v[174:175]
	v_cndmask_b32_e32 v94, v205, v94, vcc
	v_cmp_lt_i32_e32 vcc, -1, v228
	v_pk_add_f32 v[80:81], v[80:81], v[172:173]
	v_pk_add_f32 v[78:79], v[78:79], v[216:217]
	v_cndmask_b32_e32 v93, v205, v93, vcc
	v_cmp_lt_i32_e32 vcc, -1, v229
	v_pk_add_f32 v[76:77], v[76:77], v[196:197]
	v_pk_add_f32 v[74:75], v[74:75], v[192:193]
	v_cndmask_b32_e32 v92, v205, v92, vcc
	v_cmp_lt_i32_e32 vcc, -1, v226
	v_pk_add_f32 v[72:73], v[72:73], v[188:189]
	v_pk_add_f32 v[70:71], v[70:71], v[184:185]
	v_cndmask_b32_e32 v91, v205, v91, vcc
	v_cmp_lt_i32_e32 vcc, -1, v227
	v_pk_add_f32 v[68:69], v[68:69], v[180:181]
	v_pk_add_f32 v[66:67], v[66:67], v[176:177]
	v_cndmask_b32_e32 v90, v205, v90, vcc
	v_cmp_lt_i32_e32 vcc, -1, v224
	v_pk_add_f32 v[64:65], v[64:65], v[168:169]
	s_nop 0
	v_cndmask_b32_e32 v89, v205, v89, vcc
	v_cmp_lt_i32_e32 vcc, -1, v225
	s_nop 1
	v_cndmask_b32_e32 v88, v205, v88, vcc
	v_cmp_lt_i32_e32 vcc, -1, v222
	s_nop 1
	v_cndmask_b32_e32 v87, v205, v87, vcc
	v_cmp_lt_i32_e32 vcc, -1, v223
	s_nop 1
	v_cndmask_b32_e32 v86, v205, v86, vcc
	v_cmp_lt_i32_e32 vcc, -1, v220
	s_nop 1
	v_cndmask_b32_e32 v85, v205, v85, vcc
	v_cmp_lt_i32_e32 vcc, -1, v221
	s_nop 1
	v_cndmask_b32_e32 v84, v205, v84, vcc
	v_cmp_lt_i32_e32 vcc, -1, v218
	s_nop 1
	v_cndmask_b32_e32 v83, v205, v83, vcc
	v_cmp_lt_i32_e32 vcc, -1, v219
	s_nop 1
	v_cndmask_b32_e32 v82, v205, v82, vcc
	v_cmp_lt_i32_e32 vcc, -1, v161
	s_nop 1
	v_cndmask_b32_e32 v81, v205, v81, vcc
	v_cmp_lt_i32_e32 vcc, -1, v171
	s_nop 1
	v_cndmask_b32_e32 v80, v205, v80, vcc
	v_cmp_lt_i32_e32 vcc, 31, v230
	s_nop 1
	v_cndmask_b32_e32 v79, v205, v79, vcc
	v_cmp_lt_i32_e32 vcc, 31, v144
	s_nop 1
	v_cndmask_b32_e32 v78, v205, v78, vcc
	v_cmp_lt_i32_e32 vcc, 31, v228
	s_nop 1
	v_cndmask_b32_e32 v77, v205, v77, vcc
	v_cmp_lt_i32_e32 vcc, 31, v229
	s_nop 1
	v_cndmask_b32_e32 v76, v205, v76, vcc
	v_cmp_lt_i32_e32 vcc, 31, v226
	s_nop 1
	v_cndmask_b32_e32 v75, v205, v75, vcc
	v_cmp_lt_i32_e32 vcc, 31, v227
	s_nop 1
	v_cndmask_b32_e32 v74, v205, v74, vcc
	v_cmp_lt_i32_e32 vcc, 31, v224
	s_nop 1
	v_cndmask_b32_e32 v73, v205, v73, vcc
	v_cmp_lt_i32_e32 vcc, 31, v225
	s_nop 1
	v_cndmask_b32_e32 v72, v205, v72, vcc
	v_cmp_lt_i32_e32 vcc, 31, v222
	s_nop 1
	v_cndmask_b32_e32 v71, v205, v71, vcc
	v_cmp_lt_i32_e32 vcc, 31, v223
	s_nop 1
	v_cndmask_b32_e32 v70, v205, v70, vcc
	v_cmp_lt_i32_e32 vcc, 31, v220
	s_nop 1
	v_cndmask_b32_e32 v69, v205, v69, vcc
	v_cmp_lt_i32_e32 vcc, 31, v221
	s_nop 1
	v_cndmask_b32_e32 v68, v205, v68, vcc
	v_cmp_lt_i32_e32 vcc, 31, v218
	s_nop 1
	v_cndmask_b32_e32 v67, v205, v67, vcc
	v_cmp_lt_i32_e32 vcc, 31, v219
	s_nop 1
	v_cndmask_b32_e32 v66, v205, v66, vcc
	v_cmp_lt_i32_e32 vcc, 31, v161
	s_nop 1
	v_cndmask_b32_e32 v65, v205, v65, vcc
	v_cmp_lt_i32_e32 vcc, 31, v171
	s_nop 1
	v_cndmask_b32_e32 v64, v205, v64, vcc

; __device__ __forceinline__ void moba_unit(int b, int h, int j, const bf16_t* Q, const bf16_t* K, const bf16_t* VT, bf16_t* O, const float* biasd, const float* kmean, ALAS unsigned char* lds) {
;     ...
;     const size_t tok0 = (size_t)b * SEQ;
;     ALAS float* bt = (ALAS float*)(lds + 36864);
;     if (tid < 256) bt[tid] = biasd[h * 256 + tid];
;     const float cb = biasd[h * 256 + 255];
;     { const int n = tid >> 5, d2 = (tid & 31) * 2; const float* kmp = kmean + (size_t)(b * 16 + n) * 2048 + h * 64 + d2; const float v0 = kmp[0] + kmp[1024], v1 = kmp[1] + kmp[1025];
;       const unsigned wh = cvtpk(v0, v1); const float h0 = __uint_as_float(wh << 16), h1 = __uint_as_float(wh & 0xffff0000u); const unsigned wl = cvtpk(v0 - h0, v1 - h1);
;       *(ALAS unsigned*)(lds + 37888 + n * ROWB + d2 * 2) = wh; *(ALAS unsigned*)(lds + 40192 + n * ROWB + d2 * 2) = wl; }
;     bf16x8 qf[4];
;     { const bf16_t* qp = Q + (tok0 + qpos) * 1024 + h * 64 + hi * 8;
; #pragma unroll
;       for (int d0 = 0; d0 < 4; ++d0) qf[d0] = *(const bf16x8*)(qp + d0 * 16); }
;     const int NT = 4 * (j + 1);
;     const int key = tid >> 3, part = tid & 7;
;     const bf16_t* kg = K + (tok0 + key) * 1024 + h * 64 + part * 8; const int kl = key * ROWB + part * 16;
;     const bf16_t* vg = VT + (size_t)(h * 64 + key) * MTOK + tok0 + part * 8; const int vl = 9216 + key * ROWB + part * 16;
;     u32x4 kr, vr;
;     { const int kb0 = 256 * j; kr = *(const u32x4*)(kg + (size_t)kb0 * 1024); vr = *(const u32x4*)(vg + kb0); }
;     __syncthreads();
;     unsigned selmask = 0u;
;     {
;         f32x16 g;
; #pragma unroll
;         for (int r = 0; r < 16; ++r) g[r] = 0.f;
;         const ALAS unsigned char* kp = lds + 37888 + (r32 & 15) * ROWB + hi * 16;
; #pragma unroll
;         for (int d0 = 0; d0 < 4; ++d0) {
;             const bf16x8 ah = *(const ALAS bf16x8*)(kp + d0 * 32), al = *(const ALAS bf16x8*)(kp + 2304 + d0 * 32);
;             g = __builtin_amdgcn_mfma_f32_32x32x16_bf16(ah, qf[d0], g, 0, 0, 0);
;             g = __builtin_amdgcn_mfma_f32_32x32x16_bf16(al, qf[d0], g, 0, 0, 0);
;         }
;         float gv[16];
; #pragma unroll
;         for (int r = 0; r < 8; ++r) { const float own = g[r], oth = __shfl_xor(own, 32); const int n0 = (r & 3) + 8 * (r >> 2);
;             gv[n0] = hi ? oth : own; gv[n0 + 4] = hi ? own : oth; }
;     ...
;     for (int t = 0; t < NT; ++t) {
.LBB0_524:
	s_or_b64 exec, exec, s[0:1]
	s_ashr_i32 s7, s36, 7
	s_and_b32 s0, s36, 1
	s_and_b32 s7, s7, -4
	s_bfe_u32 s10, s36, 0x30005
	s_or_b32 s0, s7, s0
	s_lshl_b32 s4, s10, 12
	s_and_b32 s1, s36, 0x100
	s_xor_b32 s7, s0, 3
	v_ashrrev_i32_e32 v6, 5, v10
	v_lshlrev_b32_e32 v2, 1, v10
	s_cmp_eq_u32 s1, 0
	v_and_b32_e32 v7, 62, v2
	v_lshl_add_u32 v2, s10, 4, v6
	s_cselect_b32 s37, s0, s7
	s_waitcnt lgkmcnt(0)
	v_ashrrev_i32_e32 v3, 31, v2
	v_readlane_b32 s0, v255, 14
	v_lshlrev_b64 v[2:3], 13, v[2:3]
	v_readlane_b32 s1, v255, 15
	s_waitcnt lgkmcnt(0)
	v_lshl_add_u64 v[0:1], v[144:145], 2, s[96:97]
	v_lshlrev_b32_e32 v144, 2, v7
	v_lshl_add_u64 v[2:3], s[0:1], 0, v[2:3]
	s_lshl_b32 s0, s6, 8
	s_mov_b32 s1, s5
	v_lshl_add_u64 v[2:3], v[2:3], 0, s[0:1]
	v_lshl_add_u64 v[2:3], v[2:3], 0, v[144:145]
	s_movk_i32 s0, 0x1000
	v_add_co_u32_e32 v4, vcc, s0, v2
	s_mov_b64 s[74:75], s[96:97]
	s_nop 0
	v_addc_co_u32_e32 v5, vcc, 0, v3, vcc
	global_load_dwordx2 v[12:13], v[2:3], off
	global_load_dwordx2 v[14:15], v[4:5], off
	s_lshl_b32 s96, s37, 8
	s_lshl_b32 s0, s38, 5
	v_and_b32_e32 v11, 31, v10
	s_add_i32 s1, s0, s96
	v_or_b32_e32 v90, s1, v11
	v_ashrrev_i32_e32 v91, 31, v90
	v_lshl_add_u64 v[88:89], v[90:91], 0, s[4:5]
	v_lshlrev_b64 v[2:3], 11, v[88:89]
	v_bfe_u32 v48, v10, 5, 1
	v_lshl_add_u64 v[2:3], s[80:81], 0, v[2:3]
	s_lshl_b32 s8, s6, 7
	s_mov_b32 s9, s5
	v_lshl_add_u64 v[2:3], v[2:3], 0, s[8:9]
	v_lshlrev_b32_e32 v144, 4, v48
	v_lshl_add_u64 v[4:5], v[2:3], 0, v[144:145]
	global_load_dwordx4 v[64:67], v[4:5], off
	global_load_dwordx4 v[68:71], v[4:5], off offset:32
	global_load_dwordx4 v[72:75], v[4:5], off offset:64
	v_ashrrev_i32_e32 v8, 3, v10
	v_ashrrev_i32_e32 v9, 31, v8
	v_and_b32_e32 v2, 7, v10
	global_load_dword v99, v[0:1], off offset:1020
	s_movk_i32 s39, 0x90
	v_lshl_add_u64 v[0:1], v[8:9], 0, s[4:5]
	v_mul_lo_u32 v6, v6, s39
	v_lshlrev_b32_e32 v92, 4, v2
	v_lshlrev_b32_e32 v2, 1, v7
	v_lshlrev_b64 v[0:1], 11, v[0:1]
	s_lshl_b32 s58, s6, 6
	v_and_b32_e32 v3, 15, v10
	v_add3_u32 v9, 0, v6, v2
	v_lshl_add_u64 v[0:1], s[82:83], 0, v[0:1]
	v_add_u32_e32 v2, s58, v8
	v_mov_b32_e32 v93, v145
	v_mul_u32_u24_e32 v16, 0x90, v3
	v_lshl_add_u64 v[0:1], v[0:1], 0, s[8:9]
	v_ashrrev_i32_e32 v3, 31, v2
	s_ashr_i32 s97, s96, 31
	v_lshl_add_u64 v[94:95], v[0:1], 0, v[92:93]
	v_lshlrev_b64 v[0:1], 16, v[2:3]
	s_lshl_b64 s[6:7], s[96:97], 11
	v_lshl_add_u64 v[6:7], s[20:21], 0, v[0:1]
	v_lshl_add_u64 v[0:1], v[94:95], 0, s[6:7]
	global_load_dwordx4 v[0:3], v[0:1], off
	s_nop 0
	global_load_dwordx4 v[76:79], v[4:5], off offset:96
	v_add3_u32 v20, 0, v16, v144
	s_lshl_b32 s4, s10, 13
	v_lshl_add_u64 v[4:5], v[6:7], 0, s[4:5]
	v_lshl_add_u64 v[96:97], v[4:5], 0, v[92:93]
	v_lshl_add_u64 v[4:5], s[96:97], 1, v[96:97]
	global_load_dwordx4 v[4:7], v[4:5], off
	v_lshlrev_b32_e32 v98, 3, v48
	s_cmp_lt_i32 s37, 0
	s_waitcnt vmcnt(7)
	v_pk_add_f32 v[12:13], v[12:13], v[14:15]
	s_nop 0
	v_cvt_pk_bf16_f32 v16, v12, v13
	v_lshlrev_b32_e32 v14, 16, v16
	v_and_b32_e32 v15, 0xffff0000, v16
	v_pk_add_f32 v[12:13], v[12:13], v[14:15] neg_lo:[0,1] neg_hi:[0,1]
	s_nop 0
	v_cvt_pk_bf16_f32 v12, v12, v13
	ds_write2st64_b32 v9, v16, v12 offset0:148 offset1:157
	s_waitcnt lgkmcnt(0)
	s_barrier
	ds_read_b128 v[12:15], v20 offset:37888
	s_waitcnt vmcnt(6) lgkmcnt(0)
	v_mfma_f32_32x32x16_bf16 v[32:47], v[12:15], v[64:67], 0
	ds_read_b128 v[12:15], v20 offset:40192
	v_xor_b32_e32 v9, 32, v203
	s_waitcnt lgkmcnt(0)
	v_mfma_f32_32x32x16_bf16 v[32:47], v[12:15], v[64:67], v[32:47]
	ds_read_b128 v[12:15], v20 offset:37920
	s_waitcnt vmcnt(5) lgkmcnt(0)
	v_mfma_f32_32x32x16_bf16 v[32:47], v[12:15], v[68:71], v[32:47]
	ds_read_b128 v[12:15], v20 offset:40224
	s_waitcnt lgkmcnt(0)
	v_mfma_f32_32x32x16_bf16 v[32:47], v[12:15], v[68:71], v[32:47]
	ds_read_b128 v[12:15], v20 offset:37952
	ds_read_b128 v[16:19], v20 offset:40256
	s_waitcnt vmcnt(4) lgkmcnt(1)
	v_mfma_f32_32x32x16_bf16 v[32:47], v[12:15], v[72:75], v[32:47]
	ds_read_b128 v[12:15], v20 offset:37984
	s_waitcnt lgkmcnt(1)
	v_mfma_f32_32x32x16_bf16 v[32:47], v[16:19], v[72:75], v[32:47]
	ds_read_b128 v[16:19], v20 offset:40288
	s_waitcnt vmcnt(1) lgkmcnt(1)
	v_mfma_f32_32x32x16_bf16 v[32:47], v[12:15], v[76:79], v[32:47]
	v_and_b32_e32 v12, 64, v203
	v_add_u32_e32 v12, 64, v12
	v_cmp_lt_i32_e32 vcc, v9, v12
	s_nop 1
	v_cndmask_b32_e32 v9, v203, v9, vcc
	v_lshlrev_b32_e32 v93, 2, v9
	s_waitcnt lgkmcnt(0)
	v_mfma_f32_32x32x16_bf16 v[32:47], v[16:19], v[76:79], v[32:47]
	s_nop 11
	ds_bpermute_b32 v42, v93, v32
	ds_bpermute_b32 v50, v93, v33
	ds_bpermute_b32 v49, v93, v34
	ds_bpermute_b32 v47, v93, v35
	ds_bpermute_b32 v46, v93, v36
	ds_bpermute_b32 v45, v93, v37
	ds_bpermute_b32 v43, v93, v38
	ds_bpermute_b32 v44, v93, v39
	s_cbranch_scc1 .LBB0_516
	v_mul_lo_u32 v104, v8, s39
	s_or_b32 s4, s96, 64
	v_add3_u32 v8, 0, v104, v92
	s_lshl_b64 s[6:7], s[4:5], 11
	ds_write_b128 v8, v[0:3]
	s_waitcnt vmcnt(0)
	ds_write_b128 v8, v[4:7] offset:9216
	v_lshl_add_u64 v[0:1], v[94:95], 0, s[6:7]
	s_mov_b32 s97, s5
	s_waitcnt lgkmcnt(0)
	s_barrier
	v_lshl_add_u64 v[2:3], s[96:97], 1, v[96:97]
	global_load_dwordx4 v[80:83], v[0:1], off
	global_load_dwordx4 v[84:87], v[2:3], off offset:128
	v_lshlrev_b32_e32 v1, 1, v11
	v_lshrrev_b32_e32 v2, 1, v10
	v_and_b32_e32 v0, 19, v10
	v_and_b32_e32 v1, 8, v1
	v_and_b32_e32 v2, 4, v2
	s_sub_i32 s4, s1, 63
	v_or3_b32 v0, v2, v0, v1
	v_mul_u32_u24_e32 v105, 0x90, v0
	s_cmp_lt_i32 s38, 0
	v_mul_u32_u24_e32 v106, 0x90, v11
	s_cbranch_scc1 .LBB0_530
; #define ALAS __attribute__((address_space(3)))
; __device__ __forceinline__ int kperm(int i) { return (i & 19) | ((i & 4) << 1) | ((i & 8) >> 1); }
; template <int OFF> __device__ __forceinline__ void ldsr(bf16x8& d, unsigned a) { asm volatile("ds_read_b128 %0, %1 offset:%c2" : "=v"(d) : "v"(a), "i"(OFF) : "memory"); }
; __device__ __forceinline__ void lds_wait8(bf16x8 (&a)[8]) { asm volatile("s_waitcnt lgkmcnt(0)" : "+v"(a[0]), "+v"(a[1]), "+v"(a[2]), "+v"(a[3]), "+v"(a[4]), "+v"(a[5]), "+v"(a[6]), "+v"(a[7]) :: "memory"); }
; __device__ __forceinline__ void qk_tile(f32x16& s0, f32x16& s1, float ci, const ALAS unsigned char* Kb, const bf16x8 (&qf)[4], int r32, int hi) {
;     const unsigned p0 = (unsigned)(uintptr_t)(Kb + kperm(r32) * ROWB + hi * 16);
;     bf16x8 a[8];
;     ldsr<0>(a[0], p0); ldsr<32 * ROWB>(a[1], p0); ldsr<32>(a[2], p0); ldsr<32 * ROWB + 32>(a[3], p0);
;     ldsr<64>(a[4], p0); ldsr<32 * ROWB + 64>(a[5], p0); ldsr<96>(a[6], p0); ldsr<32 * ROWB + 96>(a[7], p0);
; #pragma unroll
;     for (int r = 0; r < 16; ++r) { s0[r] = ci; s1[r] = ci; }
;     lds_wait8(a); __builtin_amdgcn_sched_barrier(0);
; #pragma unroll
;     for (int d0 = 0; d0 < 4; ++d0) {
;         s0 = __builtin_amdgcn_mfma_f32_32x32x16_bf16(a[2 * d0], qf[d0], s0, 0, 0, 0);
;         s1 = __builtin_amdgcn_mfma_f32_32x32x16_bf16(a[2 * d0 + 1], qf[d0], s1, 0, 0, 0);
;     }
; __device__ __forceinline__ void moba_unit(int b, int h, int j, const bf16_t* Q, const bf16_t* K, const bf16_t* VT, bf16_t* O, const float* biasd, const float* kmean, ALAS unsigned char* lds) {
;     ...
;         const bool own = t < 4; const int n = own ? j : ((t - 4) >> 2); const int kbase = own ? (256 * j + 64 * t) : (64 * (t - 4));
;         const bool sel = own ? true : (((selmask >> n) & 1u) != 0u);
;         const bool active = own ? (64 * t <= 32 * wid + 31) : (__any(sel) != 0);
;         if (active) {
;             const bool nearb = (q0 - (kbase + 63)) < 128;
;             f32x16 s0, s1; const float ci = sel ? ((nearb ? 0.f : cb) - mref) : NEG;
;             qk_tile(s0, s1, ci, buf, qf, r32, hi);
;             if (nearb) near_bias(s0, s1, bt, qpos, kbase, hi);
	v_add3_u32 v1, 0, v105, v144
	ds_read_b128 v[52:55], v1 offset:0
	ds_read_b128 v[56:59], v1 offset:4608
	ds_read_b128 v[60:63], v1 offset:32
	ds_read_b128 v[100:103], v1 offset:4640
	ds_read_b128 v[108:111], v1 offset:64
	ds_read_b128 v[112:115], v1 offset:4672
	s_sub_i32 s1, s4, s96
	ds_read_b128 v[116:119], v1 offset:96
	s_cmpk_gt_i32 s1, 0x7f
	ds_read_b128 v[120:123], v1 offset:4704
	s_cselect_b64 vcc, -1, 0
	v_cndmask_b32_e32 v0, 0, v99, vcc
	v_mov_b32_e32 v1, v0
	v_mov_b32_e32 v2, v0
	v_mov_b32_e32 v3, v0
	v_mov_b32_e32 v4, v0
	v_mov_b32_e32 v5, v0
	v_mov_b32_e32 v6, v0
	v_mov_b32_e32 v7, v0
	v_mov_b32_e32 v8, v0
	v_mov_b32_e32 v9, v0
	v_mov_b32_e32 v10, v0
	v_mov_b32_e32 v11, v0
	v_mov_b32_e32 v12, v0
	v_mov_b32_e32 v13, v0
	v_mov_b32_e32 v14, v0
	v_mov_b32_e32 v15, v0
	s_waitcnt lgkmcnt(6)
	s_nop 1
	v_mfma_f32_32x32x16_bf16 v[16:31], v[52:55], v[64:67], v[0:15]
	s_and_b64 vcc, exec, vcc
	v_mfma_f32_32x32x16_bf16 v[0:15], v[56:59], v[64:67], v[0:15]
	s_waitcnt lgkmcnt(4)
	v_mfma_f32_32x32x16_bf16 v[16:31], v[60:63], v[68:71], v[16:31]
	v_mfma_f32_32x32x16_bf16 v[0:15], v[100:103], v[68:71], v[0:15]
	s_waitcnt lgkmcnt(2)
	v_mfma_f32_32x32x16_bf16 v[16:31], v[108:111], v[72:75], v[16:31]
	v_mfma_f32_32x32x16_bf16 v[0:15], v[112:115], v[72:75], v[0:15]
	s_waitcnt lgkmcnt(0)
	v_mfma_f32_32x32x16_bf16 v[16:31], v[116:119], v[76:79], v[16:31]
	v_mfma_f32_32x32x16_bf16 v[0:15], v[120:123], v[76:79], v[0:15]
	s_cbranch_vccnz .LBB0_528
	v_or_b32_e32 v51, s96, v98
	v_xad_u32 v107, v51, -1, v90
	v_med3_i32 v52, v107, 0, v204
	v_lshl_add_u32 v53, v52, 2, 0
	v_max_i32_e32 v52, 32, v107
	v_subrev_u32_e32 v52, 32, v52
	v_min_u32_e32 v52, 0xff, v52
	v_or_b32_e32 v55, 2, v51
	v_lshl_add_u32 v54, v52, 2, 0
	v_or_b32_e32 v52, 3, v51
	v_sub_u32_e32 v123, v90, v55
	v_sub_u32_e32 v122, v90, v52
	v_med3_i32 v52, v123, 0, v204
	v_lshl_add_u32 v55, v52, 2, 0
	v_max_i32_e32 v52, 32, v123
	v_subrev_u32_e32 v52, 32, v52
	v_min_u32_e32 v52, 0xff, v52
	v_sub_u32_e32 v91, v90, v51
	v_lshl_add_u32 v56, v52, 2, 0
	v_max_i32_e32 v52, 32, v122
	v_max_i32_e32 v41, 32, v91
	v_subrev_u32_e32 v52, 32, v52
	v_subrev_u32_e32 v41, 32, v41
	v_min_u32_e32 v52, 0xff, v52
	v_med3_i32 v40, v91, 0, v204
	v_min_u32_e32 v41, 0xff, v41
	v_lshl_add_u32 v57, v52, 2, 0
	v_med3_i32 v52, v122, 0, v204
	v_lshl_add_u32 v40, v40, 2, 0
	v_lshl_add_u32 v41, v41, 2, 0
	v_lshl_add_u32 v58, v52, 2, 0
	ds_read_b32 v52, v40 offset:36864
	ds_read_b32 v40, v41 offset:36864
	ds_read_b32 v53, v53 offset:36864
	ds_read_b32 v41, v54 offset:36864
	ds_read_b32 v54, v55 offset:36864
	ds_read_b32 v56, v56 offset:36864
	ds_read_b32 v57, v57 offset:36864
	ds_read_b32 v55, v58 offset:36864
	v_or_b32_e32 v58, 5, v51
	v_sub_u32_e32 v124, v90, v58
	v_max_i32_e32 v60, 32, v124
	v_subrev_u32_e32 v60, 32, v60
	v_min_u32_e32 v60, 0xff, v60
	v_lshl_add_u32 v61, v60, 2, 0
	v_med3_i32 v60, v124, 0, v204
	v_or_b32_e32 v63, 6, v51
	v_lshl_add_u32 v62, v60, 2, 0
	v_or_b32_e32 v60, 7, v51
	v_sub_u32_e32 v127, v90, v63
	v_sub_u32_e32 v126, v90, v60
	v_med3_i32 v60, v127, 0, v204
	v_lshl_add_u32 v63, v60, 2, 0
	v_max_i32_e32 v60, 32, v127
	v_subrev_u32_e32 v60, 32, v60
	v_or_b32_e32 v59, 4, v51
	v_min_u32_e32 v60, 0xff, v60
	v_sub_u32_e32 v125, v90, v59
	v_lshl_add_u32 v100, v60, 2, 0
	v_max_i32_e32 v60, 32, v126
	v_max_i32_e32 v59, 32, v125
	v_subrev_u32_e32 v60, 32, v60
	v_subrev_u32_e32 v59, 32, v59
	v_min_u32_e32 v60, 0xff, v60
	v_med3_i32 v58, v125, 0, v204
	v_min_u32_e32 v59, 0xff, v59
	v_lshl_add_u32 v101, v60, 2, 0
	v_med3_i32 v60, v126, 0, v204
	v_lshl_add_u32 v58, v58, 2, 0
	v_lshl_add_u32 v59, v59, 2, 0
	v_lshl_add_u32 v102, v60, 2, 0
	ds_read_b32 v58, v58 offset:36864
	ds_read_b32 v60, v59 offset:36864
	ds_read_b32 v61, v61 offset:36864
	ds_read_b32 v59, v62 offset:36864
	ds_read_b32 v62, v63 offset:36864
	ds_read_b32 v100, v100 offset:36864
	ds_read_b32 v101, v101 offset:36864
	ds_read_b32 v63, v102 offset:36864
	v_or_b32_e32 v102, 17, v51
	v_sub_u32_e32 v128, v90, v102
	v_max_i32_e32 v108, 32, v128
	v_subrev_u32_e32 v108, 32, v108
	v_min_u32_e32 v108, 0xff, v108
	v_lshl_add_u32 v109, v108, 2, 0
	v_med3_i32 v108, v128, 0, v204
	v_or_b32_e32 v111, 18, v51
	v_lshl_add_u32 v110, v108, 2, 0
	v_or_b32_e32 v108, 19, v51
	v_sub_u32_e32 v131, v90, v111
	v_sub_u32_e32 v130, v90, v108
	v_med3_i32 v108, v131, 0, v204
	v_lshl_add_u32 v111, v108, 2, 0
	v_max_i32_e32 v108, 32, v131
	v_subrev_u32_e32 v108, 32, v108
	v_or_b32_e32 v103, 16, v51
	v_min_u32_e32 v108, 0xff, v108
	v_sub_u32_e32 v129, v90, v103
	v_lshl_add_u32 v112, v108, 2, 0
	v_max_i32_e32 v108, 32, v130
	v_max_i32_e32 v103, 32, v129
	v_subrev_u32_e32 v108, 32, v108
	v_subrev_u32_e32 v103, 32, v103
	v_min_u32_e32 v108, 0xff, v108
	v_med3_i32 v102, v129, 0, v204
	v_min_u32_e32 v103, 0xff, v103
	v_lshl_add_u32 v113, v108, 2, 0
	v_med3_i32 v108, v130, 0, v204
	v_lshl_add_u32 v102, v102, 2, 0
	v_lshl_add_u32 v103, v103, 2, 0
	v_lshl_add_u32 v114, v108, 2, 0
	ds_read_b32 v102, v102 offset:36864
	ds_read_b32 v108, v103 offset:36864
	ds_read_b32 v109, v109 offset:36864
	ds_read_b32 v103, v110 offset:36864
	ds_read_b32 v110, v111 offset:36864
	ds_read_b32 v112, v112 offset:36864
	ds_read_b32 v113, v113 offset:36864
	ds_read_b32 v111, v114 offset:36864
	v_or_b32_e32 v114, 21, v51
	v_sub_u32_e32 v132, v90, v114
	v_max_i32_e32 v116, 32, v132
	v_subrev_u32_e32 v116, 32, v116
	v_min_u32_e32 v116, 0xff, v116
	v_lshl_add_u32 v117, v116, 2, 0
	v_med3_i32 v116, v132, 0, v204
	v_or_b32_e32 v115, 20, v51
	v_lshl_add_u32 v118, v116, 2, 0
	v_or_b32_e32 v116, 23, v51
	v_or_b32_e32 v51, 22, v51
	v_sub_u32_e32 v51, v90, v51
	v_sub_u32_e32 v134, v90, v116
	v_med3_i32 v116, v51, 0, v204
	v_lshl_add_u32 v119, v116, 2, 0
	v_max_i32_e32 v116, 32, v51
	v_subrev_u32_e32 v116, 32, v116
	v_sub_u32_e32 v133, v90, v115
	v_min_u32_e32 v116, 0xff, v116
	v_max_i32_e32 v115, 32, v133
	v_lshl_add_u32 v120, v116, 2, 0
	v_max_i32_e32 v116, 32, v134
	v_subrev_u32_e32 v115, 32, v115
	v_subrev_u32_e32 v116, 32, v116
	v_med3_i32 v114, v133, 0, v204
	v_min_u32_e32 v115, 0xff, v115
	v_min_u32_e32 v116, 0xff, v116
	v_lshl_add_u32 v114, v114, 2, 0
	v_lshl_add_u32 v115, v115, 2, 0
	v_lshl_add_u32 v121, v116, 2, 0
	v_med3_i32 v116, v134, 0, v204
	v_lshl_add_u32 v135, v116, 2, 0
	ds_read_b32 v114, v114 offset:36864
	ds_read_b32 v116, v115 offset:36864
	ds_read_b32 v117, v117 offset:36864
	ds_read_b32 v115, v118 offset:36864
	ds_read_b32 v118, v119 offset:36864
	ds_read_b32 v120, v120 offset:36864
	ds_read_b32 v121, v121 offset:36864
	ds_read_b32 v119, v135 offset:36864
	v_cmp_lt_i32_e32 vcc, -1, v134
	s_waitcnt lgkmcnt(4)
; __device__ __forceinline__ void near_bias(f32x16& s0, f32x16& s1, const ALAS float* bt, int qpos, int kbase, int hi) {
;     ...
;         const int d0 = qpos - (kbase + (r & 7) + 8 * hi + 16 * (r >> 3)), d1 = d0 - 32;
;         const float b0 = bt[min(max(d0, 0), 255)], b1 = bt[min(max(d1, 0), 255)];
;         s0[r] = d0 < 0 ? NEG : s0[r] + b0; s1[r] = d1 < 0 ? NEG : s1[r] + b1;
	v_pk_add_f32 v[28:29], v[28:29], v[114:115]
	v_pk_add_f32 v[26:27], v[26:27], v[110:111]
	v_pk_add_f32 v[24:25], v[24:25], v[102:103]
	s_waitcnt lgkmcnt(0)
	v_pk_add_f32 v[30:31], v[30:31], v[118:119]
	v_pk_add_f32 v[22:23], v[22:23], v[62:63]
	v_cndmask_b32_e32 v31, v205, v31, vcc
	v_cmp_lt_i32_e32 vcc, -1, v51
	v_pk_add_f32 v[20:21], v[20:21], v[58:59]
	v_pk_add_f32 v[18:19], v[18:19], v[54:55]
	v_cndmask_b32_e32 v30, v205, v30, vcc
	v_cmp_lt_i32_e32 vcc, -1, v132
	v_pk_add_f32 v[16:17], v[16:17], v[52:53]
	v_pk_add_f32 v[14:15], v[14:15], v[120:121]
	v_cndmask_b32_e32 v29, v205, v29, vcc
	v_cmp_lt_i32_e32 vcc, -1, v133
	v_pk_add_f32 v[12:13], v[12:13], v[116:117]
	v_pk_add_f32 v[10:11], v[10:11], v[112:113]
	v_cndmask_b32_e32 v28, v205, v28, vcc
	v_cmp_lt_i32_e32 vcc, -1, v130
	v_pk_add_f32 v[8:9], v[8:9], v[108:109]
	v_pk_add_f32 v[6:7], v[6:7], v[100:101]
	v_cndmask_b32_e32 v27, v205, v27, vcc
	v_cmp_lt_i32_e32 vcc, -1, v131
	v_pk_add_f32 v[4:5], v[4:5], v[60:61]
	v_pk_add_f32 v[2:3], v[2:3], v[56:57]
	v_cndmask_b32_e32 v26, v205, v26, vcc
	v_cmp_lt_i32_e32 vcc, -1, v128
	v_pk_add_f32 v[0:1], v[0:1], v[40:41]
	s_nop 0
	v_cndmask_b32_e32 v25, v205, v25, vcc
	v_cmp_lt_i32_e32 vcc, -1, v129
	s_nop 1
	v_cndmask_b32_e32 v24, v205, v24, vcc
	v_cmp_lt_i32_e32 vcc, -1, v126
	s_nop 1
	v_cndmask_b32_e32 v23, v205, v23, vcc
	v_cmp_lt_i32_e32 vcc, -1, v127
	s_nop 1
	v_cndmask_b32_e32 v22, v205, v22, vcc
	v_cmp_lt_i32_e32 vcc, -1, v124
	s_nop 1
	v_cndmask_b32_e32 v21, v205, v21, vcc
	v_cmp_lt_i32_e32 vcc, -1, v125
	s_nop 1
	v_cndmask_b32_e32 v20, v205, v20, vcc
	v_cmp_lt_i32_e32 vcc, -1, v122
	s_nop 1
	v_cndmask_b32_e32 v19, v205, v19, vcc
	v_cmp_lt_i32_e32 vcc, -1, v123
	s_nop 1
	v_cndmask_b32_e32 v18, v205, v18, vcc
	v_cmp_lt_i32_e32 vcc, -1, v107
	s_nop 1
	v_cndmask_b32_e32 v17, v205, v17, vcc
	v_cmp_lt_i32_e32 vcc, -1, v91
	s_nop 1
	v_cndmask_b32_e32 v16, v205, v16, vcc
	v_cmp_lt_i32_e32 vcc, 31, v134
	s_nop 1
	v_cndmask_b32_e32 v15, v205, v15, vcc
	v_cmp_lt_i32_e32 vcc, 31, v51
	s_nop 1
	v_cndmask_b32_e32 v14, v205, v14, vcc
	v_cmp_lt_i32_e32 vcc, 31, v132
	s_nop 1
	v_cndmask_b32_e32 v13, v205, v13, vcc
	v_cmp_lt_i32_e32 vcc, 31, v133
	s_nop 1
	v_cndmask_b32_e32 v12, v205, v12, vcc
	v_cmp_lt_i32_e32 vcc, 31, v130
	s_nop 1
	v_cndmask_b32_e32 v11, v205, v11, vcc
	v_cmp_lt_i32_e32 vcc, 31, v131
	s_nop 1
	v_cndmask_b32_e32 v10, v205, v10, vcc
	v_cmp_lt_i32_e32 vcc, 31, v128
	s_nop 1
	v_cndmask_b32_e32 v9, v205, v9, vcc
	v_cmp_lt_i32_e32 vcc, 31, v129
	s_nop 1
	v_cndmask_b32_e32 v8, v205, v8, vcc
	v_cmp_lt_i32_e32 vcc, 31, v126
	s_nop 1
	v_cndmask_b32_e32 v7, v205, v7, vcc
	v_cmp_lt_i32_e32 vcc, 31, v127
	s_nop 1
	v_cndmask_b32_e32 v6, v205, v6, vcc
	v_cmp_lt_i32_e32 vcc, 31, v124
	s_nop 1
	v_cndmask_b32_e32 v5, v205, v5, vcc
	v_cmp_lt_i32_e32 vcc, 31, v125
	s_nop 1
	v_cndmask_b32_e32 v4, v205, v4, vcc
	v_cmp_lt_i32_e32 vcc, 31, v122
	s_nop 1
	v_cndmask_b32_e32 v3, v205, v3, vcc
	v_cmp_lt_i32_e32 vcc, 31, v123
	s_nop 1
	v_cndmask_b32_e32 v2, v205, v2, vcc
	v_cmp_lt_i32_e32 vcc, 31, v107
	s_nop 1
	v_cndmask_b32_e32 v1, v205, v1, vcc
	v_cmp_lt_i32_e32 vcc, 31, v91
	s_nop 1
	v_cndmask_b32_e32 v0, v205, v0, vcc

; #define ALAS __attribute__((address_space(3)))
; __device__ __forceinline__ int kperm(int i) { return (i & 19) | ((i & 4) << 1) | ((i & 8) >> 1); }
; template <int OFF> __device__ __forceinline__ void ldsr(bf16x8& d, unsigned a) { asm volatile("ds_read_b128 %0, %1 offset:%c2" : "=v"(d) : "v"(a), "i"(OFF) : "memory"); }
; __device__ __forceinline__ void lds_wait8(bf16x8 (&a)[8]) { asm volatile("s_waitcnt lgkmcnt(0)" : "+v"(a[0]), "+v"(a[1]), "+v"(a[2]), "+v"(a[3]), "+v"(a[4]), "+v"(a[5]), "+v"(a[6]), "+v"(a[7]) :: "memory"); }
; __device__ __forceinline__ void qk_tile(f32x16& s0, f32x16& s1, float ci, const ALAS unsigned char* Kb, const bf16x8 (&qf)[4], int r32, int hi) {
;     const unsigned p0 = (unsigned)(uintptr_t)(Kb + kperm(r32) * ROWB + hi * 16);
;     bf16x8 a[8];
;     ldsr<0>(a[0], p0); ldsr<32 * ROWB>(a[1], p0); ldsr<32>(a[2], p0); ldsr<32 * ROWB + 32>(a[3], p0);
;     ldsr<64>(a[4], p0); ldsr<32 * ROWB + 64>(a[5], p0); ldsr<96>(a[6], p0); ldsr<32 * ROWB + 96>(a[7], p0);
; #pragma unroll
;     for (int r = 0; r < 16; ++r) { s0[r] = ci; s1[r] = ci; }
;     lds_wait8(a); __builtin_amdgcn_sched_barrier(0);
; #pragma unroll
;     for (int d0 = 0; d0 < 4; ++d0) {
;         s0 = __builtin_amdgcn_mfma_f32_32x32x16_bf16(a[2 * d0], qf[d0], s0, 0, 0, 0);
;         s1 = __builtin_amdgcn_mfma_f32_32x32x16_bf16(a[2 * d0 + 1], qf[d0], s1, 0, 0, 0);
;     }
; __device__ __forceinline__ void moba_unit(int b, int h, int j, const bf16_t* Q, const bf16_t* K, const bf16_t* VT, bf16_t* O, const float* biasd, const float* kmean, ALAS unsigned char* lds) {
;     ...
;         const bool own = t < 4; const int n = own ? j : ((t - 4) >> 2); const int kbase = own ? (256 * j + 64 * t) : (64 * (t - 4));
;         const bool sel = own ? true : (((selmask >> n) & 1u) != 0u);
;         const bool active = own ? (64 * t <= 32 * wid + 31) : (__any(sel) != 0);
;         if (active) {
;             const bool nearb = (q0 - (kbase + 63)) < 128;
;             f32x16 s0, s1; const float ci = sel ? ((nearb ? 0.f : cb) - mref) : NEG;
;             qk_tile(s0, s1, ci, buf, qf, r32, hi);
;             if (nearb) near_bias(s0, s1, bt, qpos, kbase, hi);
.LBB0_542:
	v_add3_u32 v33, s17, v105, v144
	ds_read_b128 v[108:111], v33 offset:0
	s_add_i32 s10, s18, 0x100
	ds_read_b128 v[112:115], v33 offset:4608
	s_and_b64 s[8:9], s[6:7], exec
	ds_read_b128 v[116:119], v33 offset:32
	s_cselect_b32 s8, s10, s15
	ds_read_b128 v[120:123], v33 offset:4640
	s_or_b64 vcc, s[6:7], s[0:1]
	s_sub_i32 s0, s4, s8
	ds_read_b128 v[124:127], v33 offset:64
	s_cmpk_gt_i32 s0, 0x7f
	ds_read_b128 v[128:131], v33 offset:4672
	s_cselect_b64 s[0:1], -1, 0
	ds_read_b128 v[132:135], v33 offset:96
	v_cndmask_b32_e64 v32, 0, v99, s[0:1]
	ds_read_b128 v[136:139], v33 offset:4704
	v_sub_f32_e32 v32, v32, v101
	v_cndmask_b32_e32 v32, v205, v32, vcc
	v_mov_b32_e32 v33, v32
	v_mov_b32_e32 v34, v32
	v_mov_b32_e32 v35, v32
	v_mov_b32_e32 v36, v32
	v_mov_b32_e32 v37, v32
	v_mov_b32_e32 v38, v32
	v_mov_b32_e32 v39, v32
	v_mov_b32_e32 v40, v32
	v_mov_b32_e32 v41, v32
	v_mov_b32_e32 v42, v32
	v_mov_b32_e32 v43, v32
	v_mov_b32_e32 v44, v32
	v_mov_b32_e32 v45, v32
	v_mov_b32_e32 v46, v32
	v_mov_b32_e32 v47, v32
	s_waitcnt lgkmcnt(6)
	s_nop 1
	v_mfma_f32_32x32x16_bf16 v[48:63], v[108:111], v[64:67], v[32:47]
	s_and_b64 vcc, exec, s[0:1]
	v_mfma_f32_32x32x16_bf16 v[32:47], v[112:115], v[64:67], v[32:47]
	s_waitcnt lgkmcnt(4)
	v_mfma_f32_32x32x16_bf16 v[48:63], v[116:119], v[68:71], v[48:63]
	v_mfma_f32_32x32x16_bf16 v[32:47], v[120:123], v[68:71], v[32:47]
	s_waitcnt lgkmcnt(2)
	v_mfma_f32_32x32x16_bf16 v[48:63], v[124:127], v[72:75], v[48:63]
	v_mfma_f32_32x32x16_bf16 v[32:47], v[128:131], v[72:75], v[32:47]
	s_waitcnt lgkmcnt(0)
	v_mfma_f32_32x32x16_bf16 v[48:63], v[132:135], v[76:79], v[48:63]
	v_mfma_f32_32x32x16_bf16 v[32:47], v[136:139], v[76:79], v[32:47]
	s_cbranch_vccnz .LBB0_544
	v_or_b32_e32 v130, s8, v98
	v_xad_u32 v139, v130, -1, v90
	v_med3_i32 v108, v139, 0, v204
	v_lshl_add_u32 v109, v108, 2, 0
	v_max_i32_e32 v108, 32, v139
	v_subrev_u32_e32 v108, 32, v108
	v_min_u32_e32 v108, 0xff, v108
	v_or_b32_e32 v111, 2, v130
	v_lshl_add_u32 v110, v108, 2, 0
	v_or_b32_e32 v108, 3, v130
	v_sub_u32_e32 v141, v90, v111
	v_sub_u32_e32 v140, v91, v108
	v_med3_i32 v108, v141, 0, v204
	v_lshl_add_u32 v111, v108, 2, 0
	v_max_i32_e32 v108, 32, v141
	v_subrev_u32_e32 v108, 32, v108
	v_min_u32_e32 v108, 0xff, v108
	v_sub_u32_e32 v138, v90, v130
	v_lshl_add_u32 v112, v108, 2, 0
	v_max_i32_e32 v108, 32, v140
	v_max_i32_e32 v103, 32, v138
	v_subrev_u32_e32 v108, 32, v108
	v_subrev_u32_e32 v103, 32, v103
	v_min_u32_e32 v108, 0xff, v108
	v_med3_i32 v102, v138, 0, v204
	v_min_u32_e32 v103, 0xff, v103
	v_lshl_add_u32 v113, v108, 2, 0
	v_med3_i32 v108, v140, 0, v204
	v_lshl_add_u32 v102, v102, 2, 0
	v_lshl_add_u32 v103, v103, 2, 0
	v_lshl_add_u32 v114, v108, 2, 0
	ds_read_b32 v108, v102 offset:36864
	ds_read_b32 v102, v103 offset:36864
	ds_read_b32 v109, v109 offset:36864
	ds_read_b32 v103, v110 offset:36864
	ds_read_b32 v110, v111 offset:36864
	ds_read_b32 v112, v112 offset:36864
	ds_read_b32 v113, v113 offset:36864
	ds_read_b32 v111, v114 offset:36864
	v_or_b32_e32 v114, 5, v130
	v_sub_u32_e32 v142, v91, v114
	v_max_i32_e32 v116, 32, v142
	v_subrev_u32_e32 v116, 32, v116
	v_min_u32_e32 v116, 0xff, v116
	v_lshl_add_u32 v117, v116, 2, 0
	v_med3_i32 v116, v142, 0, v204
	v_or_b32_e32 v119, 6, v130
	v_lshl_add_u32 v118, v116, 2, 0
	v_or_b32_e32 v116, 7, v130
	v_sub_u32_e32 v157, v90, v119
	v_sub_u32_e32 v156, v91, v116
	v_med3_i32 v116, v157, 0, v204
	v_lshl_add_u32 v119, v116, 2, 0
	v_max_i32_e32 v116, 32, v157
	v_subrev_u32_e32 v116, 32, v116
	v_or_b32_e32 v115, 4, v130
	v_min_u32_e32 v116, 0xff, v116
	v_sub_u32_e32 v143, v90, v115
	v_lshl_add_u32 v120, v116, 2, 0
	v_max_i32_e32 v116, 32, v156
	v_max_i32_e32 v115, 32, v143
	v_subrev_u32_e32 v116, 32, v116
	v_subrev_u32_e32 v115, 32, v115
	v_min_u32_e32 v116, 0xff, v116
	v_med3_i32 v114, v143, 0, v204
	v_min_u32_e32 v115, 0xff, v115
	v_lshl_add_u32 v121, v116, 2, 0
	v_med3_i32 v116, v156, 0, v204
	v_lshl_add_u32 v114, v114, 2, 0
	v_lshl_add_u32 v115, v115, 2, 0
	v_lshl_add_u32 v122, v116, 2, 0
	ds_read_b32 v114, v114 offset:36864
	ds_read_b32 v116, v115 offset:36864
	ds_read_b32 v117, v117 offset:36864
	ds_read_b32 v115, v118 offset:36864
	ds_read_b32 v118, v119 offset:36864
	ds_read_b32 v120, v120 offset:36864
	ds_read_b32 v121, v121 offset:36864
	ds_read_b32 v119, v122 offset:36864
	v_or_b32_e32 v122, 17, v130
	v_sub_u32_e32 v158, v91, v122
	v_max_i32_e32 v124, 32, v158
	v_subrev_u32_e32 v124, 32, v124
	v_min_u32_e32 v124, 0xff, v124
	v_lshl_add_u32 v125, v124, 2, 0
	v_med3_i32 v124, v158, 0, v204
	v_or_b32_e32 v127, 18, v130
	v_lshl_add_u32 v126, v124, 2, 0
	v_or_b32_e32 v124, 19, v130
	v_sub_u32_e32 v161, v90, v127
	v_sub_u32_e32 v160, v91, v124
	v_med3_i32 v124, v161, 0, v204
	v_lshl_add_u32 v127, v124, 2, 0
	v_max_i32_e32 v124, 32, v161
	v_subrev_u32_e32 v124, 32, v124
	v_or_b32_e32 v123, 16, v130
	v_min_u32_e32 v124, 0xff, v124
	v_sub_u32_e32 v159, v90, v123
	v_lshl_add_u32 v128, v124, 2, 0
	v_max_i32_e32 v124, 32, v160
	v_max_i32_e32 v123, 32, v159
	v_subrev_u32_e32 v124, 32, v124
	v_subrev_u32_e32 v123, 32, v123
	v_min_u32_e32 v124, 0xff, v124
	v_med3_i32 v122, v159, 0, v204
	v_min_u32_e32 v123, 0xff, v123
	v_lshl_add_u32 v129, v124, 2, 0
	v_med3_i32 v124, v160, 0, v204
	v_lshl_add_u32 v122, v122, 2, 0
	v_lshl_add_u32 v123, v123, 2, 0
	v_lshl_add_u32 v131, v124, 2, 0
	ds_read_b32 v122, v122 offset:36864
	ds_read_b32 v124, v123 offset:36864
	ds_read_b32 v125, v125 offset:36864
	ds_read_b32 v123, v126 offset:36864
	ds_read_b32 v126, v127 offset:36864
	ds_read_b32 v128, v128 offset:36864
	ds_read_b32 v129, v129 offset:36864
	ds_read_b32 v127, v131 offset:36864
	v_or_b32_e32 v131, 21, v130
	v_or_b32_e32 v132, 20, v130
	v_or_b32_e32 v135, 23, v130
	v_or_b32_e32 v130, 22, v130
	v_sub_u32_e32 v165, v90, v130
	v_med3_i32 v130, v165, 0, v204
	v_sub_u32_e32 v164, v91, v135
	v_lshl_add_u32 v135, v130, 2, 0
	v_max_i32_e32 v130, 32, v165
	v_subrev_u32_e32 v130, 32, v130
	v_sub_u32_e32 v162, v91, v131
	v_sub_u32_e32 v163, v90, v132
	v_min_u32_e32 v130, 0xff, v130
	v_max_i32_e32 v132, 32, v163
	v_max_i32_e32 v133, 32, v162
	v_lshl_add_u32 v136, v130, 2, 0
	v_max_i32_e32 v130, 32, v164
	v_subrev_u32_e32 v132, 32, v132
	v_subrev_u32_e32 v133, 32, v133
	v_subrev_u32_e32 v130, 32, v130
	v_med3_i32 v131, v163, 0, v204
	v_min_u32_e32 v132, 0xff, v132
	v_min_u32_e32 v133, 0xff, v133
	v_med3_i32 v134, v162, 0, v204
	v_min_u32_e32 v130, 0xff, v130
	v_lshl_add_u32 v131, v131, 2, 0
	v_lshl_add_u32 v132, v132, 2, 0
	v_lshl_add_u32 v133, v133, 2, 0
	v_lshl_add_u32 v134, v134, 2, 0
	v_lshl_add_u32 v137, v130, 2, 0
	v_med3_i32 v130, v164, 0, v204
	v_lshl_add_u32 v166, v130, 2, 0
	ds_read_b32 v130, v131 offset:36864
	ds_read_b32 v132, v132 offset:36864
	ds_read_b32 v133, v133 offset:36864
	ds_read_b32 v131, v134 offset:36864
	ds_read_b32 v134, v135 offset:36864
	ds_read_b32 v136, v136 offset:36864
	ds_read_b32 v137, v137 offset:36864
	ds_read_b32 v135, v166 offset:36864
	v_cmp_lt_i32_e32 vcc, -1, v164
	s_waitcnt lgkmcnt(4)
; #define ALAS __attribute__((address_space(3)))
; __device__ __forceinline__ void near_bias(f32x16& s0, f32x16& s1, const ALAS float* bt, int qpos, int kbase, int hi) {
; #pragma unroll
;     for (int r = 0; r < 16; ++r) {
;         const int d0 = qpos - (kbase + (r & 7) + 8 * hi + 16 * (r >> 3)), d1 = d0 - 32;
;         const float b0 = bt[min(max(d0, 0), 255)], b1 = bt[min(max(d1, 0), 255)];
;         s0[r] = d0 < 0 ? NEG : s0[r] + b0; s1[r] = d1 < 0 ? NEG : s1[r] + b1;
;     }
; }
	v_pk_add_f32 v[60:61], v[60:61], v[130:131]
	v_pk_add_f32 v[58:59], v[58:59], v[126:127]
	v_pk_add_f32 v[56:57], v[56:57], v[122:123]
	s_waitcnt lgkmcnt(0)
	v_pk_add_f32 v[62:63], v[62:63], v[134:135]
	v_pk_add_f32 v[54:55], v[54:55], v[118:119]
	v_cndmask_b32_e32 v63, v205, v63, vcc
	v_cmp_lt_i32_e32 vcc, -1, v165
	v_pk_add_f32 v[52:53], v[52:53], v[114:115]
	v_pk_add_f32 v[50:51], v[50:51], v[110:111]
	v_cndmask_b32_e32 v62, v205, v62, vcc
	v_cmp_lt_i32_e32 vcc, -1, v162
	v_pk_add_f32 v[48:49], v[48:49], v[108:109]
	v_pk_add_f32 v[46:47], v[46:47], v[136:137]
	v_cndmask_b32_e32 v61, v205, v61, vcc
	v_cmp_lt_i32_e32 vcc, -1, v163
	v_pk_add_f32 v[44:45], v[44:45], v[132:133]
	v_pk_add_f32 v[42:43], v[42:43], v[128:129]
	v_cndmask_b32_e32 v60, v205, v60, vcc
	v_cmp_lt_i32_e32 vcc, -1, v160
	v_pk_add_f32 v[40:41], v[40:41], v[124:125]
	v_pk_add_f32 v[38:39], v[38:39], v[120:121]
	v_cndmask_b32_e32 v59, v205, v59, vcc
	v_cmp_lt_i32_e32 vcc, -1, v161
	v_pk_add_f32 v[36:37], v[36:37], v[116:117]
	v_pk_add_f32 v[34:35], v[34:35], v[112:113]
	v_cndmask_b32_e32 v58, v205, v58, vcc
	v_cmp_lt_i32_e32 vcc, -1, v158
	v_pk_add_f32 v[32:33], v[32:33], v[102:103]
	s_nop 0
	v_cndmask_b32_e32 v57, v205, v57, vcc
	v_cmp_lt_i32_e32 vcc, -1, v159
	s_nop 1
	v_cndmask_b32_e32 v56, v205, v56, vcc
	v_cmp_lt_i32_e32 vcc, -1, v156
	s_nop 1
	v_cndmask_b32_e32 v55, v205, v55, vcc
	v_cmp_lt_i32_e32 vcc, -1, v157
	s_nop 1
	v_cndmask_b32_e32 v54, v205, v54, vcc
	v_cmp_lt_i32_e32 vcc, -1, v142
	s_nop 1
	v_cndmask_b32_e32 v53, v205, v53, vcc
	v_cmp_lt_i32_e32 vcc, -1, v143
	s_nop 1
	v_cndmask_b32_e32 v52, v205, v52, vcc
	v_cmp_lt_i32_e32 vcc, -1, v140
	s_nop 1
	v_cndmask_b32_e32 v51, v205, v51, vcc
	v_cmp_lt_i32_e32 vcc, -1, v141
	s_nop 1
	v_cndmask_b32_e32 v50, v205, v50, vcc
	v_cmp_lt_i32_e32 vcc, -1, v139
	s_nop 1
	v_cndmask_b32_e32 v49, v205, v49, vcc
	v_cmp_lt_i32_e32 vcc, -1, v138
	s_nop 1
	v_cndmask_b32_e32 v48, v205, v48, vcc
	v_cmp_lt_i32_e32 vcc, 31, v164
	s_nop 1
	v_cndmask_b32_e32 v47, v205, v47, vcc
	v_cmp_lt_i32_e32 vcc, 31, v165
	s_nop 1
	v_cndmask_b32_e32 v46, v205, v46, vcc
	v_cmp_lt_i32_e32 vcc, 31, v162
	s_nop 1
	v_cndmask_b32_e32 v45, v205, v45, vcc
	v_cmp_lt_i32_e32 vcc, 31, v163
	s_nop 1
	v_cndmask_b32_e32 v44, v205, v44, vcc
	v_cmp_lt_i32_e32 vcc, 31, v160
	s_nop 1
	v_cndmask_b32_e32 v43, v205, v43, vcc
	v_cmp_lt_i32_e32 vcc, 31, v161
	s_nop 1
	v_cndmask_b32_e32 v42, v205, v42, vcc
	v_cmp_lt_i32_e32 vcc, 31, v158
	s_nop 1
	v_cndmask_b32_e32 v41, v205, v41, vcc
	v_cmp_lt_i32_e32 vcc, 31, v159
	s_nop 1
	v_cndmask_b32_e32 v40, v205, v40, vcc
	v_cmp_lt_i32_e32 vcc, 31, v156
	s_nop 1
	v_cndmask_b32_e32 v39, v205, v39, vcc
	v_cmp_lt_i32_e32 vcc, 31, v157
	s_nop 1
	v_cndmask_b32_e32 v38, v205, v38, vcc
	v_cmp_lt_i32_e32 vcc, 31, v142
	s_nop 1
	v_cndmask_b32_e32 v37, v205, v37, vcc
	v_cmp_lt_i32_e32 vcc, 31, v143
	s_nop 1
	v_cndmask_b32_e32 v36, v205, v36, vcc
	v_cmp_lt_i32_e32 vcc, 31, v140
	s_nop 1
	v_cndmask_b32_e32 v35, v205, v35, vcc
	v_cmp_lt_i32_e32 vcc, 31, v141
	s_nop 1
	v_cndmask_b32_e32 v34, v205, v34, vcc
	v_cmp_lt_i32_e32 vcc, 31, v139
	s_nop 1
	v_cndmask_b32_e32 v33, v205, v33, vcc
	v_cmp_lt_i32_e32 vcc, 31, v138
	s_nop 1
	v_cndmask_b32_e32 v32, v205, v32, vcc
